# RWKV scan re-partitioned to 128 blocks x 8 rows, 2 keys per lane, hand-written pipelined step loop
# speedup vs baseline: 1.1794x; 1.0037x over previous
.LBB0_250:
	s_cmp_gt_i32 s81, 10
	s_mov_b64 s[4:5], -1
	s_cbranch_scc0 .LBB0_688
	s_mov_b32 s82, s2
	s_cmpk_gt_i32 s82, 0x7f
	s_cbranch_scc0 .LBB0_545
	s_cmpk_gt_u32 s82, 0xff
	s_cbranch_scc1 .LBB0_544
	s_and_b32 s32, s82, 1
	s_sub_i32 s82, s82, 0x80
	s_lshr_b32 s82, s82, 1
	s_add_i32 s82, s82, 0x80
	s_add_i32 s22, s82, 0xffffff80
	s_mov_b64 s[18:19], s[84:85]
	v_readlane_b32 s4, v255, 17
	v_mov_b32_e32 v116, v119
	s_lshr_b32 s36, s22, 5
	s_and_b32 s4, s4, 6
	s_waitcnt lgkmcnt(0)
	s_load_dwordx2 s[20:21], s[18:19], 0x120
	s_or_b32 s14, s36, s4
	s_load_dwordx2 s[10:11], s[18:19], 0x58
	s_load_dwordx2 s[12:13], s[18:19], 0x68
	s_load_dwordx4 s[4:7], s[18:19], 0x78
	s_load_dwordx2 s[16:17], s[18:19], 0x88
	s_bfe_u32 s35, s82, 0x30002
	v_readlane_b32 s9, v255, 18
	s_lshl_b32 s8, s14, 9
	s_lshl_b32 s34, s35, 6
	s_lshl_b32 s9, s9, 11
	s_waitcnt lgkmcnt(0)
	s_add_u32 s23, s4, s9
	s_addc_u32 s24, s5, 0
	s_add_u32 s25, s6, s9
	s_addc_u32 s26, s7, 0
	s_add_u32 s4, s16, s9
	s_movk_i32 s9, 0x80
	s_addc_u32 s5, s17, 0
	v_cmp_gt_u32_e64 s[16:17], s9, v116
	s_waitcnt vmcnt(0)
	v_mov_b32_e32 v0, 0x70
	v_mov_b32_e32 v1, 0x60
	v_cndmask_b32_e64 v16, v0, v1, s[16:17]
	v_lshl_add_u64 v[0:1], s[18:19], 0, v[16:17]
	global_load_dwordx2 v[0:1], v[0:1], off
	s_lshl_b32 s52, s35, 8
	v_bfe_u32 v139, v116, 4, 2
	s_add_u32 s6, s4, s52
	s_mov_b32 s15, s53
	v_and_b32_e32 v140, 15, v116
	s_addc_u32 s7, s5, 0
	s_lshl_b64 s[14:15], s[14:15], 17
	v_lshlrev_b32_e32 v20, 12, v139
	v_or_b32_e32 v2, v20, v140
	v_lshlrev_b32_e32 v16, 2, v2
	v_or_b32_e32 v19, 0x400, v20
	v_or_b32_e32 v18, 0x600, v20
	v_or_b32_e32 v15, 0x800, v20
	v_or_b32_e32 v14, 0xa00, v20
	v_or_b32_e32 v13, 0xc00, v20
	v_or_b32_e32 v12, 0xe00, v20
	v_or_b32_e32 v6, 0x4000, v20
	v_or_b32_e32 v11, 0x4200, v20
	v_or_b32_e32 v10, 0x4400, v20
	v_or_b32_e32 v9, 0x4600, v20
	v_or_b32_e32 v8, 0x4800, v20
	v_or_b32_e32 v7, 0x4a00, v20
	v_or_b32_e32 v21, 16, v140
	s_and_b32 s38, s82, 3
	s_mov_b32 s9, s53
	v_lshlrev_b32_e32 v122, 2, v140
	v_mov_b32_e32 v123, v17
	s_movk_i32 s4, 0x7f
	v_cmp_lt_u32_e64 s[4:5], s4, v116
	s_waitcnt vmcnt(0)
	v_lshl_add_u64 v[0:1], v[0:1], 0, s[14:15]
	v_lshl_add_u64 v[0:1], v[0:1], 0, s[52:53]
	v_lshl_add_u64 v[2:3], v[0:1], 0, v[16:17]
	global_load_dword v4, v[2:3], off
	s_waitcnt vmcnt(0)
	v_cvt_pk_bf16_f32 v141, v4, v17
	global_load_dword v4, v[2:3], off offset:2048
	s_waitcnt vmcnt(0)
	v_cvt_pk_bf16_f32 v142, v4, v17
	v_or_b32_e32 v4, v19, v140
	v_lshlrev_b32_e32 v16, 2, v4
	v_lshl_add_u64 v[4:5], v[0:1], 0, v[16:17]
	global_load_dword v4, v[4:5], off
	s_waitcnt vmcnt(0)
	v_cvt_pk_bf16_f32 v143, v4, v17
	v_or_b32_e32 v4, v18, v140
	v_lshlrev_b32_e32 v16, 2, v4
	v_lshl_add_u64 v[4:5], v[0:1], 0, v[16:17]
	global_load_dword v4, v[4:5], off
	s_waitcnt vmcnt(0)
	v_cvt_pk_bf16_f32 v145, v4, v17
	v_or_b32_e32 v4, v15, v140
	v_lshlrev_b32_e32 v16, 2, v4
	v_lshl_add_u64 v[4:5], v[0:1], 0, v[16:17]
	global_load_dword v4, v[4:5], off
	s_waitcnt vmcnt(0)
	v_cvt_pk_bf16_f32 v147, v4, v17
	v_or_b32_e32 v4, v14, v140
	v_lshlrev_b32_e32 v16, 2, v4
	v_lshl_add_u64 v[4:5], v[0:1], 0, v[16:17]
	global_load_dword v4, v[4:5], off
	s_waitcnt vmcnt(0)
	v_cvt_pk_bf16_f32 v149, v4, v17
	v_or_b32_e32 v4, v13, v140
	v_lshlrev_b32_e32 v16, 2, v4
	v_lshl_add_u64 v[4:5], v[0:1], 0, v[16:17]
	global_load_dword v4, v[4:5], off
	s_waitcnt vmcnt(0)
	v_cvt_pk_bf16_f32 v151, v4, v17
	v_or_b32_e32 v4, v12, v140
	v_lshlrev_b32_e32 v16, 2, v4
	v_lshl_add_u64 v[4:5], v[0:1], 0, v[16:17]
	global_load_dword v4, v[4:5], off
	s_waitcnt vmcnt(0)
	v_cvt_pk_bf16_f32 v153, v4, v17
	v_or_b32_e32 v4, v6, v140
	v_lshlrev_b32_e32 v16, 2, v4
	v_lshl_add_u64 v[4:5], v[0:1], 0, v[16:17]
	global_load_dword v4, v[4:5], off
	s_waitcnt vmcnt(0)
	v_cvt_pk_bf16_f32 v144, v4, v17
	v_or_b32_e32 v4, v11, v140
	v_lshlrev_b32_e32 v16, 2, v4
	v_lshl_add_u64 v[4:5], v[0:1], 0, v[16:17]
	global_load_dword v4, v[4:5], off
	s_waitcnt vmcnt(0)
	v_cvt_pk_bf16_f32 v146, v4, v17
	v_or_b32_e32 v4, v10, v140
	v_lshlrev_b32_e32 v16, 2, v4
	v_lshl_add_u64 v[4:5], v[0:1], 0, v[16:17]
	global_load_dword v4, v[4:5], off
	s_waitcnt vmcnt(0)
	v_cvt_pk_bf16_f32 v148, v4, v17
	v_or_b32_e32 v4, v9, v140
	v_lshlrev_b32_e32 v16, 2, v4
	v_lshl_add_u64 v[4:5], v[0:1], 0, v[16:17]
	global_load_dword v4, v[4:5], off
	s_waitcnt vmcnt(0)
	v_cvt_pk_bf16_f32 v150, v4, v17
	v_or_b32_e32 v4, v8, v140
	v_lshlrev_b32_e32 v16, 2, v4
	v_lshl_add_u64 v[4:5], v[0:1], 0, v[16:17]
	global_load_dword v4, v[4:5], off
	s_waitcnt vmcnt(0)
	v_cvt_pk_bf16_f32 v152, v4, v17
	v_or_b32_e32 v4, v7, v140
	v_lshlrev_b32_e32 v16, 2, v4
	v_lshl_add_u64 v[4:5], v[0:1], 0, v[16:17]
	global_load_dword v4, v[4:5], off
	v_or_b32_e32 v5, 0x4c00, v20
	s_waitcnt vmcnt(0)
	v_cvt_pk_bf16_f32 v154, v4, v17
	v_or_b32_e32 v4, v5, v140
	v_lshlrev_b32_e32 v16, 2, v4
	v_lshl_add_u64 v[22:23], v[0:1], 0, v[16:17]
	global_load_dword v4, v[22:23], off
	s_waitcnt vmcnt(0)
	v_cvt_pk_bf16_f32 v155, v4, v17
	v_or_b32_e32 v4, 0x4e00, v20
	v_or_b32_e32 v16, v4, v140
	v_lshlrev_b32_e32 v16, 2, v16
	v_lshl_add_u64 v[22:23], v[0:1], 0, v[16:17]
	global_load_dword v16, v[22:23], off
	s_waitcnt vmcnt(0)
	v_cvt_pk_bf16_f32 v156, v16, v17
	global_load_dword v16, v[2:3], off offset:64
	s_waitcnt vmcnt(0)
	v_cvt_pk_bf16_f32 v157, v16, v17
	v_or_b32_e32 v16, v20, v21
	v_lshlrev_b32_e32 v16, 2, v16
	v_lshl_add_u64 v[22:23], v[0:1], 0, v[16:17]
	global_load_dword v16, v[22:23], off offset:2048
	s_waitcnt vmcnt(0)
	v_cvt_pk_bf16_f32 v158, v16, v17
	v_or_b32_e32 v16, v19, v21
	v_lshlrev_b32_e32 v16, 2, v16
	v_lshl_add_u64 v[22:23], v[0:1], 0, v[16:17]
	global_load_dword v16, v[22:23], off
	s_waitcnt vmcnt(0)
	v_cvt_pk_bf16_f32 v159, v16, v17
	v_or_b32_e32 v16, v18, v21
	v_lshlrev_b32_e32 v16, 2, v16
	v_lshl_add_u64 v[22:23], v[0:1], 0, v[16:17]
	global_load_dword v16, v[22:23], off
	s_waitcnt vmcnt(0)
	v_cvt_pk_bf16_f32 v160, v16, v17
	v_or_b32_e32 v16, v15, v21
	v_lshlrev_b32_e32 v16, 2, v16
	v_lshl_add_u64 v[22:23], v[0:1], 0, v[16:17]
	global_load_dword v16, v[22:23], off
	s_waitcnt vmcnt(0)
	v_cvt_pk_bf16_f32 v161, v16, v17
	v_or_b32_e32 v16, v14, v21
	v_lshlrev_b32_e32 v16, 2, v16
	v_lshl_add_u64 v[22:23], v[0:1], 0, v[16:17]
	global_load_dword v16, v[22:23], off
	s_waitcnt vmcnt(0)
	v_cvt_pk_bf16_f32 v162, v16, v17
	v_or_b32_e32 v16, v13, v21
	v_lshlrev_b32_e32 v16, 2, v16
	v_lshl_add_u64 v[22:23], v[0:1], 0, v[16:17]
	global_load_dword v16, v[22:23], off
	s_waitcnt vmcnt(0)
	v_cvt_pk_bf16_f32 v163, v16, v17
	v_or_b32_e32 v16, v12, v21
	v_lshlrev_b32_e32 v16, 2, v16
	v_lshl_add_u64 v[22:23], v[0:1], 0, v[16:17]
	global_load_dword v16, v[22:23], off
	s_waitcnt vmcnt(0)
	v_cvt_pk_bf16_f32 v165, v16, v17
	v_or_b32_e32 v16, v6, v21
	v_lshlrev_b32_e32 v16, 2, v16
	v_lshl_add_u64 v[22:23], v[0:1], 0, v[16:17]
	global_load_dword v16, v[22:23], off
	s_waitcnt vmcnt(0)
	v_cvt_pk_bf16_f32 v164, v16, v17
	v_or_b32_e32 v16, v11, v21
	v_lshlrev_b32_e32 v16, 2, v16
	v_lshl_add_u64 v[22:23], v[0:1], 0, v[16:17]
	global_load_dword v16, v[22:23], off
	s_waitcnt vmcnt(0)
	v_cvt_pk_bf16_f32 v166, v16, v17
	v_or_b32_e32 v16, v10, v21
	v_lshlrev_b32_e32 v16, 2, v16
	v_lshl_add_u64 v[22:23], v[0:1], 0, v[16:17]
	global_load_dword v16, v[22:23], off
	s_waitcnt vmcnt(0)
	v_cvt_pk_bf16_f32 v167, v16, v17
	v_or_b32_e32 v16, v9, v21
	v_lshlrev_b32_e32 v16, 2, v16
	v_lshl_add_u64 v[22:23], v[0:1], 0, v[16:17]
	global_load_dword v16, v[22:23], off
	s_waitcnt vmcnt(0)
	v_cvt_pk_bf16_f32 v168, v16, v17
	v_or_b32_e32 v16, v8, v21
	v_lshlrev_b32_e32 v16, 2, v16
	v_lshl_add_u64 v[22:23], v[0:1], 0, v[16:17]
	global_load_dword v16, v[22:23], off
	s_waitcnt vmcnt(0)
	v_cvt_pk_bf16_f32 v169, v16, v17
	v_or_b32_e32 v16, v7, v21
	v_lshlrev_b32_e32 v16, 2, v16
	v_lshl_add_u64 v[22:23], v[0:1], 0, v[16:17]
	global_load_dword v16, v[22:23], off
	s_waitcnt vmcnt(0)
	v_cvt_pk_bf16_f32 v170, v16, v17
	v_or_b32_e32 v16, v5, v21
	v_lshlrev_b32_e32 v16, 2, v16
	v_lshl_add_u64 v[22:23], v[0:1], 0, v[16:17]
	global_load_dword v16, v[22:23], off
	s_waitcnt vmcnt(0)
	v_cvt_pk_bf16_f32 v171, v16, v17
	v_or_b32_e32 v16, v4, v21
	v_lshlrev_b32_e32 v16, 2, v16
	v_lshl_add_u64 v[22:23], v[0:1], 0, v[16:17]
	global_load_dword v16, v[22:23], off
	s_waitcnt vmcnt(0)
	v_cvt_pk_bf16_f32 v172, v16, v17
	v_or_b32_e32 v21, 32, v140
	global_load_dword v16, v[2:3], off offset:128
	s_waitcnt vmcnt(0)
	v_cvt_pk_bf16_f32 v173, v16, v17
	v_or_b32_e32 v16, v20, v21
	v_lshlrev_b32_e32 v16, 2, v16
	v_lshl_add_u64 v[22:23], v[0:1], 0, v[16:17]
	global_load_dword v16, v[22:23], off offset:2048
	s_waitcnt vmcnt(0)
	v_cvt_pk_bf16_f32 v174, v16, v17
	v_or_b32_e32 v16, v19, v21
	v_lshlrev_b32_e32 v16, 2, v16
	v_lshl_add_u64 v[22:23], v[0:1], 0, v[16:17]
	global_load_dword v16, v[22:23], off
	s_add_u32 s14, s25, s52
	global_load_dword v2, v[2:3], off offset:192
	s_waitcnt vmcnt(1)
	v_cvt_pk_bf16_f32 v176, v16, v17
	v_or_b32_e32 v16, v18, v21
	v_lshlrev_b32_e32 v16, 2, v16
	v_lshl_add_u64 v[22:23], v[0:1], 0, v[16:17]
	global_load_dword v16, v[22:23], off
	s_waitcnt vmcnt(0)
	v_cvt_pk_bf16_f32 v178, v16, v17
	v_or_b32_e32 v16, v15, v21
	v_lshlrev_b32_e32 v16, 2, v16
	v_lshl_add_u64 v[22:23], v[0:1], 0, v[16:17]
	global_load_dword v16, v[22:23], off
	s_waitcnt vmcnt(0)
	v_cvt_pk_bf16_f32 v180, v16, v17
	v_or_b32_e32 v16, v14, v21
	v_lshlrev_b32_e32 v16, 2, v16
	v_lshl_add_u64 v[22:23], v[0:1], 0, v[16:17]
	global_load_dword v16, v[22:23], off
	s_waitcnt vmcnt(0)
	v_cvt_pk_bf16_f32 v182, v16, v17
	v_or_b32_e32 v16, v13, v21
	v_lshlrev_b32_e32 v16, 2, v16
	v_lshl_add_u64 v[22:23], v[0:1], 0, v[16:17]
	global_load_dword v16, v[22:23], off
	s_waitcnt vmcnt(0)
	v_cvt_pk_bf16_f32 v184, v16, v17
	v_or_b32_e32 v16, v12, v21
	v_lshlrev_b32_e32 v16, 2, v16
	v_lshl_add_u64 v[22:23], v[0:1], 0, v[16:17]
	global_load_dword v16, v[22:23], off
	s_waitcnt vmcnt(0)
	v_cvt_pk_bf16_f32 v186, v16, v17
	v_or_b32_e32 v16, v6, v21
	v_lshlrev_b32_e32 v16, 2, v16
	v_lshl_add_u64 v[22:23], v[0:1], 0, v[16:17]
	global_load_dword v16, v[22:23], off
	s_waitcnt vmcnt(0)
	v_cvt_pk_bf16_f32 v175, v16, v17
	v_or_b32_e32 v16, v11, v21
	v_lshlrev_b32_e32 v16, 2, v16
	v_lshl_add_u64 v[22:23], v[0:1], 0, v[16:17]
	global_load_dword v16, v[22:23], off
	s_waitcnt vmcnt(0)
	v_cvt_pk_bf16_f32 v177, v16, v17
	v_or_b32_e32 v16, v10, v21
	v_lshlrev_b32_e32 v16, 2, v16
	v_lshl_add_u64 v[22:23], v[0:1], 0, v[16:17]
	global_load_dword v16, v[22:23], off
	s_waitcnt vmcnt(0)
	v_cvt_pk_bf16_f32 v179, v16, v17
	v_or_b32_e32 v16, v9, v21
	v_lshlrev_b32_e32 v16, 2, v16
	v_lshl_add_u64 v[22:23], v[0:1], 0, v[16:17]
	global_load_dword v16, v[22:23], off
	s_waitcnt vmcnt(0)
	v_cvt_pk_bf16_f32 v181, v16, v17
	v_or_b32_e32 v16, v8, v21
	v_lshlrev_b32_e32 v16, 2, v16
	v_lshl_add_u64 v[22:23], v[0:1], 0, v[16:17]
	global_load_dword v16, v[22:23], off
	s_waitcnt vmcnt(0)
	v_cvt_pk_bf16_f32 v183, v16, v17
	v_or_b32_e32 v16, v7, v21
	v_lshlrev_b32_e32 v16, 2, v16
	v_lshl_add_u64 v[22:23], v[0:1], 0, v[16:17]
	global_load_dword v16, v[22:23], off
	s_waitcnt vmcnt(0)
	v_cvt_pk_bf16_f32 v185, v16, v17
	v_or_b32_e32 v16, v5, v21
	v_lshlrev_b32_e32 v16, 2, v16
	v_lshl_add_u64 v[22:23], v[0:1], 0, v[16:17]
	global_load_dword v16, v[22:23], off
	s_waitcnt vmcnt(0)
	v_cvt_pk_bf16_f32 v187, v16, v17
	v_or_b32_e32 v16, v4, v21
	v_lshlrev_b32_e32 v16, 2, v16
	v_lshl_add_u64 v[22:23], v[0:1], 0, v[16:17]
	v_or_b32_e32 v21, 48, v140
	global_load_dword v16, v[22:23], off
	v_cvt_pk_bf16_f32 v189, v2, v17
	v_or_b32_e32 v2, v20, v21
	s_waitcnt vmcnt(0)
	v_cvt_pk_bf16_f32 v188, v16, v17
	v_lshlrev_b32_e32 v16, 2, v2
	v_lshl_add_u64 v[2:3], v[0:1], 0, v[16:17]
	global_load_dword v2, v[2:3], off offset:2048
	s_waitcnt vmcnt(0)
	v_cvt_pk_bf16_f32 v190, v2, v17
	v_or_b32_e32 v2, v19, v21
	v_lshlrev_b32_e32 v16, 2, v2
	v_lshl_add_u64 v[2:3], v[0:1], 0, v[16:17]
	global_load_dword v2, v[2:3], off
	s_waitcnt vmcnt(0)
	v_cvt_pk_bf16_f32 v191, v2, v17
	v_or_b32_e32 v2, v18, v21
	v_lshlrev_b32_e32 v16, 2, v2
	v_lshl_add_u64 v[2:3], v[0:1], 0, v[16:17]
	global_load_dword v2, v[2:3], off
	s_waitcnt vmcnt(0)
	v_cvt_pk_bf16_f32 v192, v2, v17
	v_or_b32_e32 v2, v15, v21
	v_lshlrev_b32_e32 v16, 2, v2
	v_lshl_add_u64 v[2:3], v[0:1], 0, v[16:17]
	global_load_dword v2, v[2:3], off
	s_waitcnt vmcnt(0)
	v_cvt_pk_bf16_f32 v193, v2, v17
	v_or_b32_e32 v2, v14, v21
	v_lshlrev_b32_e32 v16, 2, v2
	v_lshl_add_u64 v[2:3], v[0:1], 0, v[16:17]
	global_load_dword v2, v[2:3], off
	s_waitcnt vmcnt(0)
	v_cvt_pk_bf16_f32 v194, v2, v17
	v_or_b32_e32 v2, v13, v21
	v_lshlrev_b32_e32 v16, 2, v2
	v_lshl_add_u64 v[2:3], v[0:1], 0, v[16:17]
	global_load_dword v2, v[2:3], off
	s_waitcnt vmcnt(0)
	v_cvt_pk_bf16_f32 v195, v2, v17
	v_or_b32_e32 v2, v12, v21
	v_lshlrev_b32_e32 v16, 2, v2
	v_lshl_add_u64 v[2:3], v[0:1], 0, v[16:17]
	global_load_dword v2, v[2:3], off
	s_waitcnt vmcnt(0)
	v_cvt_pk_bf16_f32 v198, v2, v17
	v_or_b32_e32 v2, v6, v21
	v_lshlrev_b32_e32 v16, 2, v2
	v_lshl_add_u64 v[2:3], v[0:1], 0, v[16:17]
	global_load_dword v2, v[2:3], off
	s_waitcnt vmcnt(0)
	v_cvt_pk_bf16_f32 v196, v2, v17
	v_or_b32_e32 v2, v11, v21
	v_lshlrev_b32_e32 v16, 2, v2
	v_lshl_add_u64 v[2:3], v[0:1], 0, v[16:17]
	global_load_dword v2, v[2:3], off
	s_waitcnt vmcnt(0)
	v_cvt_pk_bf16_f32 v197, v2, v17
	v_or_b32_e32 v2, v10, v21
	v_lshlrev_b32_e32 v16, 2, v2
	v_lshl_add_u64 v[2:3], v[0:1], 0, v[16:17]
	global_load_dword v2, v[2:3], off
	s_waitcnt vmcnt(0)
	v_cvt_pk_bf16_f32 v199, v2, v17
	v_or_b32_e32 v2, v9, v21
	v_lshlrev_b32_e32 v16, 2, v2
	v_lshl_add_u64 v[2:3], v[0:1], 0, v[16:17]
	global_load_dword v2, v[2:3], off
	s_waitcnt vmcnt(0)
	v_cvt_pk_bf16_f32 v200, v2, v17
	v_or_b32_e32 v2, v8, v21
	v_lshlrev_b32_e32 v16, 2, v2
	v_lshl_add_u64 v[2:3], v[0:1], 0, v[16:17]
	global_load_dword v2, v[2:3], off
	s_waitcnt vmcnt(0)
	v_cvt_pk_bf16_f32 v201, v2, v17
	v_or_b32_e32 v2, v7, v21
	v_lshlrev_b32_e32 v16, 2, v2
	v_lshl_add_u64 v[2:3], v[0:1], 0, v[16:17]
	global_load_dword v2, v[2:3], off
	s_waitcnt vmcnt(0)
	v_cvt_pk_bf16_f32 v202, v2, v17
	v_or_b32_e32 v2, v5, v21
	v_lshlrev_b32_e32 v16, 2, v2
	v_lshl_add_u64 v[2:3], v[0:1], 0, v[16:17]
	global_load_dword v2, v[2:3], off
	s_waitcnt vmcnt(0)
	v_cvt_pk_bf16_f32 v203, v2, v17
	v_or_b32_e32 v2, v4, v21
	v_lshlrev_b32_e32 v16, 2, v2
	v_lshl_add_u64 v[0:1], v[0:1], 0, v[16:17]
	global_load_dword v0, v[0:1], off
	s_waitcnt vmcnt(0)
	v_cvt_pk_bf16_f32 v204, v0, v17
	v_mov_b32_e32 v0, s13
	v_mov_b32_e32 v1, s11
	s_addc_u32 s15, s26, 0
	s_lshl_b32 s37, s38, 4
	v_cndmask_b32_e64 v1, v0, v1, s[16:17]
	v_mov_b32_e32 v0, s12
	v_mov_b32_e32 v2, s10
	v_cndmask_b32_e64 v0, v0, v2, s[16:17]
	s_add_u32 s58, s20, 0x6aa8000
	v_lshl_add_u64 v[0:1], s[8:9], 2, v[0:1]
	s_addc_u32 s59, s21, 0
	v_lshl_add_u64 v[0:1], v[0:1], 0, s[52:53]
	s_add_u32 s8, s23, s52
	v_lshl_add_u64 v[0:1], v[0:1], 0, v[122:123]
	s_addc_u32 s9, s24, 0
	global_load_dword v117, v[0:1], off
	global_load_dword v121, v[0:1], off offset:64
	global_load_dword v123, v[0:1], off offset:128
	global_load_dword v125, v[0:1], off offset:192
	global_load_dword v127, v122, s[8:9]
	global_load_dword v128, v122, s[14:15]
	global_load_dword v129, v122, s[6:7]
	global_load_dword v130, v122, s[8:9] offset:64
	global_load_dword v131, v122, s[14:15] offset:64
	global_load_dword v132, v122, s[6:7] offset:64
	global_load_dword v133, v122, s[8:9] offset:128
	global_load_dword v134, v122, s[14:15] offset:128
	global_load_dword v135, v122, s[6:7] offset:128
	global_load_dword v136, v122, s[8:9] offset:192
	global_load_dword v137, v122, s[14:15] offset:192
	global_load_dword v138, v122, s[6:7] offset:192
	s_or_b32 s40, s34, s37
	s_cmp_gt_u32 s22, 31
	s_cselect_b64 s[62:63], -1, 0
	s_cmp_lt_u32 s22, 32
	s_cselect_b64 s[64:65], -1, 0
	s_and_b64 s[6:7], s[64:65], exec
	s_cselect_b32 s43, 0, 0xe0
	s_lshl_b32 s6, s36, 6
	s_mov_b32 s8, 0x78787879
	s_add_i32 s41, s6, 0x5c0
	s_or_b32 s39, s6, 0x580
	s_movk_i32 s6, 0x440
	v_mov_b32_e32 v23, 0
	v_mul_hi_i32 v0, v116, s8
	s_addk_i32 s40, 0x300
	s_add_i32 s42, s34, 0x1c0
	v_cmp_gt_i32_e64 s[6:7], s6, v116
	v_lshrrev_b32_e32 v205, 31, v0
	v_ashrrev_i32_e32 v206, 4, v0
	v_mov_b32_e32 v22, v23
	v_mov_b32_e32 v21, v23
	v_mov_b32_e32 v20, v23
	s_and_saveexec_b64 s[8:9], s[6:7]
	s_cbranch_execz .LBB0_273
	v_add_u32_e32 v1, v206, v205
	s_movk_i32 s10, 0xffde
	s_waitcnt vmcnt(15)
	v_mad_u64_u32 v[2:3], s[10:11], v1, s10, v[116:117]
	v_cmp_lt_i32_e32 vcc, 7, v2
	s_and_saveexec_b64 s[10:11], vcc
	s_xor_b64 s[10:11], exec, s[10:11]
	s_cbranch_execz .LBB0_268
	v_cmp_lt_u32_e32 vcc, 15, v2
	s_and_saveexec_b64 s[12:13], vcc
	s_xor_b64 s[12:13], exec, s[12:13]
	s_cbranch_execz .LBB0_265
	v_cmp_lt_u32_e32 vcc, 23, v2
	s_and_saveexec_b64 s[14:15], vcc
	s_xor_b64 s[14:15], exec, s[14:15]
	s_cbranch_execz .LBB0_262
	v_cmp_lt_u32_e32 vcc, 31, v2
	v_lshlrev_b32_e32 v2, 3, v2
	s_and_saveexec_b64 s[18:19], vcc
	s_xor_b64 s[18:19], exec, s[18:19]
	v_add_u32_e32 v0, s40, v2
	s_andn2_saveexec_b64 s[18:19], s[18:19]
	v_add_u32_e32 v0, s41, v2
	s_or_b64 exec, exec, s[18:19]

.LBB0_421:
	s_or_b64 exec, exec, s[18:19]
	s_mul_i32 s52, s36, 0x20800
	s_xor_b64 s[76:77], s[22:23], -1
	s_lshl_b64 s[18:19], s[52:53], 2
	s_add_u32 s18, s20, s18
	v_mov_b32_e32 v6, 0xc200
	v_mov_b32_e32 v7, 0xb000
	s_addc_u32 s19, s21, s19
	v_cndmask_b32_e64 v6, v6, v7, s[16:17]
	s_lshl_b32 s16, s34, 1
	s_add_u32 s20, s20, s16
	s_addc_u32 s21, s21, 0
	s_lshl_b32 s22, s35, 2
	s_add_u32 s18, s18, s22
	s_addc_u32 s19, s19, 0
	s_add_u32 s78, s18, 0x118000
	v_readlane_b32 s18, v255, 3
	v_lshlrev_b32_e32 v4, 1, v116
	s_addc_u32 s79, s19, 0
	v_lshl_add_u32 v61, v235, 2, s18
	s_lshl_b32 s18, s37, 1
	v_and_b32_e32 v5, 14, v4
	v_lshrrev_b32_e32 v7, 2, v116
	s_add_u32 s18, s20, s18
	v_and_b32_e32 v52, 16, v7
	s_addc_u32 s19, s21, 0
	v_lshlrev_b32_e32 v16, 1, v5
	v_ashrrev_i32_e32 v87, 4, v116
	v_add_u32_e32 v64, 0, v4
	v_lshlrev_b32_e32 v67, 5, v5
	v_lshl_add_u64 v[4:5], s[18:19], 0, v[16:17]
	v_lshlrev_b32_e32 v16, 8, v52
	v_lshl_or_b32 v69, v139, 10, v16
	v_lshl_or_b32 v16, v87, 8, v122
	v_add_u32_e32 v92, 16, v87
	v_and_b32_e32 v60, 1, v116
	v_add_u32_e32 v91, 0, v16
	v_lshl_or_b32 v16, v92, 8, v122
	v_add_u32_e32 v93, 0, v16
	v_add_u32_e32 v16, 0x11200, v64
	v_cmp_eq_u32_e32 vcc, 0, v60
	v_or_b32_e32 v7, v52, v140
	v_mul_u32_u24_e32 v7, 0x90, v7
	v_cndmask_b32_e32 v98, v61, v16, vcc
	v_add_u32_e32 v16, 0x11000, v64
	v_cndmask_b32_e32 v99, v61, v16, vcc
	v_add_u32_e32 v16, 0x10e00, v64
	v_cndmask_b32_e32 v100, v61, v16, vcc
	v_add_u32_e32 v16, 0x10c00, v64
	v_cndmask_b32_e32 v101, v61, v16, vcc
	v_add_u32_e32 v16, 0x10a00, v64
	s_mov_b64 s[18:19], 0xe488000
	v_cndmask_b32_e32 v102, v61, v16, vcc
	v_add_u32_e32 v16, 0x10800, v64
	v_add3_u32 v62, 0, v6, v7
	v_or_b32_e32 v6, s38, v140
	v_lshl_add_u64 v[18:19], v[4:5], 0, s[18:19]
	s_mov_b32 s18, 0x5040100
	s_movk_i32 s20, 0xffde
	v_add_u32_e32 v97, v106, v105
	v_cndmask_b32_e32 v103, v61, v16, vcc
	v_add_u32_e32 v16, 0x10600, v64
	v_cmp_eq_u32_e64 s[16:17], 0, v6
	v_perm_b32 v7, v153, v151, s18
	v_perm_b32 v6, v149, v147, s18
	v_perm_b32 v5, v145, v143, s18
	v_perm_b32 v4, v142, v141, s18
	v_perm_b32 v11, v165, v163, s18
	v_perm_b32 v10, v162, v161, s18
	v_perm_b32 v9, v160, v159, s18
	v_perm_b32 v8, v158, v157, s18
	v_perm_b32 v15, v186, v184, s18
	v_perm_b32 v14, v182, v180, s18
	v_perm_b32 v13, v178, v176, s18
	v_perm_b32 v12, v174, v173, s18
	v_perm_b32 v27, v198, v195, s18
	v_perm_b32 v26, v194, v193, s18
	v_perm_b32 v25, v192, v191, s18
	v_perm_b32 v24, v190, v189, s18
	v_perm_b32 v35, v156, v155, s18
	v_perm_b32 v34, v154, v152, s18
	v_perm_b32 v33, v150, v148, s18
	v_perm_b32 v32, v146, v144, s18
	v_perm_b32 v39, v172, v171, s18
	v_perm_b32 v38, v170, v169, s18
	v_perm_b32 v37, v168, v167, s18
	v_perm_b32 v36, v166, v164, s18
	v_perm_b32 v43, v188, v187, s18
	v_perm_b32 v42, v185, v183, s18
	v_perm_b32 v41, v181, v179, s18
	v_perm_b32 v40, v177, v175, s18
	v_perm_b32 v47, v204, v203, s18
	v_perm_b32 v46, v202, v201, s18
	v_perm_b32 v45, v200, v199, s18
	v_perm_b32 v44, v197, v196, s18
	v_mad_u64_u32 v[58:59], s[18:19], v97, s20, v[104:105]
	v_cndmask_b32_e32 v104, v61, v16, vcc
	v_add_u32_e32 v16, 0x10400, v64
	v_cndmask_b32_e32 v105, v61, v16, vcc
	v_add_u32_e32 v16, 0x10200, v64
	v_cndmask_b32_e32 v106, v61, v16, vcc
	v_add_u32_e32 v16, 0x10000, v64
	v_cndmask_b32_e32 v107, v61, v16, vcc
	v_add_u32_e32 v16, 0xfe00, v64
	v_cndmask_b32_e32 v108, v61, v16, vcc
	v_add_u32_e32 v16, 0xfc00, v64
	v_cndmask_b32_e32 v109, v61, v16, vcc
	v_add_u32_e32 v16, 0xfa00, v64
	v_cndmask_b32_e32 v110, v61, v16, vcc
	v_add_u32_e32 v16, 0xf800, v64
	v_cndmask_b32_e32 v111, v61, v16, vcc
	v_add_u32_e32 v16, 0xf600, v64
	v_cndmask_b32_e32 v112, v61, v16, vcc
	v_add_u32_e32 v16, 0xf400, v64
	v_cndmask_b32_e32 v113, v61, v16, vcc
	v_add_u32_e32 v16, 0xf200, v64
	v_cndmask_b32_e32 v114, v61, v16, vcc
	v_add_u32_e32 v16, 0xf000, v64
	v_add_u32_e32 v94, v206, v205
	v_cndmask_b32_e32 v115, v61, v16, vcc
	v_add_u32_e32 v16, 0xee00, v64
	v_and_b32_e32 v63, 48, v116
	v_ashrrev_i32_e32 v90, 3, v116
	v_mad_u64_u32 v[52:53], s[18:19], v94, s20, v[116:117]
	v_cndmask_b32_e32 v116, v61, v16, vcc
	v_add_u32_e32 v16, 0xec00, v64
	v_add_u32_e32 v95, v234, v233
	v_cndmask_b32_e32 v122, v61, v16, vcc
	v_add_u32_e32 v16, 0xea00, v64
	v_mad_u64_u32 v[54:55], s[18:19], v95, s20, v[124:125]
	v_add_u32_e32 v96, v237, v236
	v_cndmask_b32_e32 v124, v61, v16, vcc
	v_add_u32_e32 v16, 0xe800, v64
	v_mad_u64_u32 v[56:57], s[18:19], v96, s20, v[126:127]
	v_cndmask_b32_e32 v126, v61, v16, vcc
	v_add_u32_e32 v16, 0xe600, v64
	v_lshl_add_u32 v88, v140, 4, 0
	v_cndmask_b32_e32 v139, v61, v16, vcc
	v_add_u32_e32 v16, 0xe400, v64
	v_mad_i32_i24 v68, v140, -12, v88
	v_cndmask_b32_e32 v140, v61, v16, vcc
	v_add_u32_e32 v16, 0xe200, v64
	v_cndmask_b32_e32 v141, v61, v16, vcc
	v_add_u32_e32 v16, 0xe000, v64
	v_cndmask_b32_e32 v142, v61, v16, vcc
	v_add_u32_e32 v16, 0xde00, v64
	v_cndmask_b32_e32 v143, v61, v16, vcc
	v_add_u32_e32 v16, 0xdc00, v64
	v_cndmask_b32_e32 v144, v61, v16, vcc
	v_add_u32_e32 v16, 0xda00, v64
	v_cndmask_b32_e32 v145, v61, v16, vcc
	v_add_u32_e32 v16, 0xd800, v64
	v_cndmask_b32_e32 v146, v61, v16, vcc
	v_add_u32_e32 v16, 0xd600, v64
	v_cndmask_b32_e32 v147, v61, v16, vcc
	v_and_b32_e32 v16, -16, v52
	v_add_u32_e32 v65, 0xd400, v64
	v_cmp_ne_u32_e64 s[18:19], 16, v16
	v_lshl_add_u32 v16, v94, 6, 0
	v_lshlrev_b32_e32 v53, 5, v52
	s_mov_b32 s28, 0x9c00
	s_movk_i32 s29, 0xc0
	s_movk_i32 s30, 0xff90
	v_cndmask_b32_e32 v148, v61, v65, vcc
	v_add3_u32 v55, v16, v53, s28
	v_mad_u64_u32 v[60:61], s[20:21], v94, s29, v[16:17]
	v_mul_lo_u32 v16, v94, s30
	v_lshlrev_b32_e32 v59, 4, v52
	v_add3_u32 v59, v60, v16, v59
	v_and_b32_e32 v16, -16, v54
	v_cmp_ne_u32_e64 s[20:21], 16, v16
	v_lshl_add_u32 v16, v95, 6, 0
	v_add_u32_e32 v53, v60, v53
	v_lshlrev_b32_e32 v64, 5, v54
	v_mad_u64_u32 v[60:61], s[22:23], v95, s29, v[16:17]
	v_add3_u32 v65, v16, v64, s28
	v_mul_lo_u32 v16, v95, s30
	v_lshlrev_b32_e32 v61, 4, v54
	v_add3_u32 v71, v60, v16, v61
	v_and_b32_e32 v16, -16, v56
	v_cmp_ne_u32_e64 s[22:23], 16, v16
	v_lshl_add_u32 v16, v96, 6, 0
	v_add_u32_e32 v64, v60, v64
	v_lshlrev_b32_e32 v72, 5, v56
	v_mad_u64_u32 v[60:61], s[24:25], v96, s29, v[16:17]
	v_add3_u32 v82, v16, v72, s28
	v_mul_lo_u32 v16, v96, s30
	v_lshlrev_b32_e32 v61, 4, v56
	v_add3_u32 v158, v60, v16, v61
	v_and_b32_e32 v16, -16, v58
	v_cmp_ne_u32_e64 s[24:25], 16, v16
	v_lshl_add_u32 v16, v97, 6, 0
	v_add_u32_e32 v83, v60, v72
	v_lshlrev_b32_e32 v72, 5, v58
	v_mad_u64_u32 v[60:61], s[26:27], v97, s29, v[16:17]
	v_add3_u32 v152, v16, v72, s28
	v_mul_lo_u32 v16, v97, s30
	v_lshlrev_b32_e32 v61, 4, v58
	v_add3_u32 v159, v60, v16, v61
	v_lshl_add_u32 v16, v86, 6, 0
	v_add_u32_e32 v153, v60, v72
	v_lshlrev_b32_e32 v72, 5, v84
	v_mad_u64_u32 v[60:61], s[26:27], v86, s29, v[16:17]
	v_add3_u32 v155, v16, v72, s28
	v_add_u32_e32 v16, v60, v72
	v_mul_lo_u32 v61, v86, s30
	v_lshlrev_b32_e32 v72, 4, v84
	v_mov_b32_e32 v149, s40
	v_mov_b32_e32 v150, s41
	v_cmp_gt_u32_e64 s[26:27], 32, v52
	v_add3_u32 v160, v60, v61, v72
	v_mov_b32_e32 v80, s42
	v_mov_b32_e32 v81, s34
	v_cmp_gt_i32_e32 vcc, 8, v52
	v_cndmask_b32_e64 v61, v149, v150, s[26:27]
	v_mov_b32_e32 v151, s39
	v_cmp_gt_u32_e64 s[26:27], 24, v52
	v_cndmask_b32_e32 v60, v80, v81, vcc
	v_cmp_gt_i32_e64 s[28:29], 16, v52
	v_cndmask_b32_e64 v61, v61, v151, s[26:27]
	v_cmp_gt_u32_e64 s[30:31], 32, v54
	v_cndmask_b32_e64 v60, v61, v60, s[28:29]
	v_lshl_add_u32 v60, v52, 3, v60
	v_ashrrev_i32_e32 v61, 31, v60
	v_lshl_add_u64 v[72:73], v[60:61], 1, s[58:59]
	v_cmp_gt_i32_e64 s[28:29], 8, v54
	v_cndmask_b32_e64 v61, v149, v150, s[30:31]
	v_cmp_gt_u32_e64 s[30:31], 24, v54
	v_cndmask_b32_e64 v60, v80, v81, s[28:29]
	v_cmp_gt_i32_e64 s[34:35], 16, v54
	v_cndmask_b32_e64 v61, v61, v151, s[30:31]
	v_cmp_gt_u32_e64 s[36:37], 32, v56
	v_cndmask_b32_e64 v60, v61, v60, s[34:35]
	v_lshl_add_u32 v60, v54, 3, v60
	v_ashrrev_i32_e32 v61, 31, v60
	v_lshl_add_u64 v[74:75], v[60:61], 1, s[58:59]
	v_cmp_gt_i32_e64 s[34:35], 8, v56
	v_cndmask_b32_e64 v61, v149, v150, s[36:37]
	v_cmp_gt_u32_e64 s[36:37], 24, v56
	v_cndmask_b32_e64 v60, v80, v81, s[34:35]
	v_cmp_gt_i32_e64 s[38:39], 16, v56
	v_cndmask_b32_e64 v61, v61, v151, s[36:37]
	v_cmp_gt_u32_e64 s[40:41], 32, v58
	v_cndmask_b32_e64 v60, v61, v60, s[38:39]
	v_lshl_add_u32 v60, v56, 3, v60
	v_ashrrev_i32_e32 v61, 31, v60
	v_lshl_add_u64 v[76:77], v[60:61], 1, s[58:59]
	v_cmp_gt_i32_e64 s[38:39], 8, v58
	v_cndmask_b32_e64 v61, v149, v150, s[40:41]
	v_cmp_gt_u32_e64 s[40:41], 24, v58
	v_cndmask_b32_e64 v60, v80, v81, s[38:39]
	v_cmp_gt_i32_e64 s[42:43], 16, v58
	v_cndmask_b32_e64 v61, v61, v151, s[40:41]
	v_cmp_gt_u32_e64 s[44:45], 32, v84
	v_cndmask_b32_e64 v60, v61, v60, s[42:43]
	v_lshl_add_u32 v60, v58, 3, v60
	v_ashrrev_i32_e32 v61, 31, v60
	v_lshl_add_u64 v[78:79], v[60:61], 1, s[58:59]
	v_cmp_gt_i32_e64 s[42:43], 8, v84
	v_cndmask_b32_e64 v61, v149, v150, s[44:45]
	v_cmp_gt_u32_e64 s[44:45], 24, v84
	v_cndmask_b32_e64 v60, v80, v81, s[42:43]
	v_cmp_gt_i32_e64 s[48:49], 16, v84
	v_cndmask_b32_e64 v61, v61, v151, s[44:45]
	v_add_u32_e32 v57, 0x1f00, v53
	v_cndmask_b32_e64 v60, v61, v60, s[48:49]
	v_cmp_gt_u32_e64 s[48:49], 16, v52
	v_add_u32_e32 v70, 0x1f00, v64
	v_add_u32_e32 v85, 0x1f00, v83
	v_cndmask_b32_e64 v52, v55, v57, s[48:49]
	v_cndmask_b32_e32 v149, v52, v53, vcc
	v_cmp_gt_u32_e32 vcc, 16, v54
	v_add_u32_e32 v154, 0x1f00, v153
	v_add_u32_e32 v156, 0x1f00, v16
	v_cndmask_b32_e32 v53, v65, v70, vcc
	v_cmp_gt_u32_e32 vcc, 16, v56
	v_lshl_add_u32 v60, v84, 3, v60
	v_mov_b32_e32 v57, 0xc080
	v_cndmask_b32_e32 v54, v82, v85, vcc
	v_cmp_gt_u32_e32 vcc, 16, v58
	v_lshl_add_u32 v66, v90, 9, 0
	v_ashrrev_i32_e32 v61, 31, v60
	v_cndmask_b32_e32 v55, v152, v154, vcc
	v_cmp_gt_u32_e32 vcc, 16, v84
	v_cndmask_b32_e64 v52, v57, v254, s[26:27]
	v_cndmask_b32_e64 v150, v53, v64, s[28:29]
	v_cndmask_b32_e32 v56, v155, v156, vcc
	v_cndmask_b32_e64 v53, v57, v254, s[30:31]
	v_cndmask_b32_e64 v151, v54, v83, s[34:35]
	v_cndmask_b32_e64 v54, v57, v254, s[36:37]
	v_cndmask_b32_e64 v152, v55, v153, s[38:39]
	v_cndmask_b32_e64 v55, v57, v254, s[40:41]
	v_cndmask_b32_e64 v153, v56, v16, s[42:43]
	v_cndmask_b32_e64 v56, v57, v254, s[44:45]
	v_mov_b32_e32 v16, v17
	v_lshl_add_u32 v89, v87, 2, 0
	v_lshl_add_u64 v[80:81], v[60:61], 1, s[58:59]
	s_mov_b32 s34, -8
	v_add_u32_e32 v154, v62, v63
	v_add_u32_e32 v155, v66, v67
	v_add_u32_e32 v156, v59, v52
	v_add_u32_e32 v157, v71, v53
	v_add_u32_e32 v158, v158, v54
	v_add_u32_e32 v159, v159, v55
	v_add_u32_e32 v160, v160, v56
	v_add_u32_e32 v161, v68, v69
	v_mov_b64_e32 v[82:83], v[16:17]
	v_mov_b64_e32 v[84:85], v[16:17]
	v_mov_b32_e32 v52, v232
	v_mov_b32_e32 v53, v231
	v_mov_b32_e32 v54, v230
	v_mov_b32_e32 v55, v207
	s_waitcnt lgkmcnt(0)
	s_barrier
	v_mad_u64_u32 v[218:219], s[26:27], v94, s83, v[72:73]
	v_mad_u64_u32 v[220:221], s[26:27], v95, s83, v[74:75]
	v_mad_u64_u32 v[222:223], s[26:27], v96, s83, v[76:77]
	v_mad_u64_u32 v[244:245], s[26:27], v97, s83, v[78:79]
	v_mad_u64_u32 v[246:247], s[26:27], v86, s83, v[80:81]
	v_and_b32_e32 v98, 31, v119
	v_lshlrev_b32_e32 v98, 3, v98
	v_lshrrev_b32_e32 v99, 5, v119
	s_lshl_b32 s26, s32, 3
	v_add_u32_e32 v99, s26, v99
	v_lshl_add_u32 v99, v99, 2, v228
	v_add_u32_e32 v99, 0x6000, v99
	v_lshrrev_b32_e32 v100, 1, v119
	v_lshlrev_b32_e32 v100, 2, v100
	v_add_u32_e32 v100, 0xd400, v100
	v_lshrrev_b32_e32 v101, 3, v119
	v_lshlrev_b32_e32 v101, 9, v101
	v_and_b32_e32 v102, 7, v119
	v_lshl_add_u32 v101, v102, 6, v101
	v_add_u32_e32 v101, 0xd400, v101
	v_sub_u32_e32 v102, s26, v102
	v_lshlrev_b32_e32 v102, 1, v102
	v_ashrrev_i32_e32 v103, 31, v102
	v_lshl_add_u64 v[102:103], v[18:19], 0, v[102:103]
	s_branch .LBB0_424

.LBB0_514:
	s_andn2_b64 vcc, exec, s[62:63]
	s_cbranch_vccnz .Lrs_fwd
	ds_read_b64 v[162:163], v98 offset:32512
	ds_read_b64 v[164:165], v98 offset:24320
	ds_read_b64 v[166:167], v98 offset:16128
	ds_read_b64 v[168:169], v98 offset:40704
	ds_read_b32 v170, v99 offset:1984
	ds_read_b64 v[174:175], v98 offset:32256
	ds_read_b64 v[176:177], v98 offset:24064
	ds_read_b64 v[178:179], v98 offset:15872
	ds_read_b64 v[180:181], v98 offset:40448
	ds_read_b32 v182, v99 offset:1920
	ds_read_b64 v[186:187], v98 offset:7936
	s_waitcnt lgkmcnt(6)
	v_pk_mul_f32 v[190:191], v[82:83], v[162:163]
	v_add_f32_e32 v196, v190, v191
	v_pk_mul_f32 v[194:195], v[82:83], v[164:165]
	s_nop 0
	v_add_f32_dpp v196, v196, v196 quad_perm:[1,0,3,2] row_mask:0xf bank_mask:0xf bound_ctrl:1
	v_pk_fma_f32 v[194:195], v[170:171], v[166:167], v[194:195] op_sel_hi:[0,1,1]
	s_nop 0
	v_add_f32_dpp v196, v196, v196 quad_perm:[2,3,0,1] row_mask:0xf bank_mask:0xf bound_ctrl:1
	s_nop 1
	v_add_f32_dpp v196, v196, v196 row_half_mirror row_mask:0xf bank_mask:0xf bound_ctrl:1
	s_nop 1
	v_add_f32_dpp v196, v196, v196 row_mirror row_mask:0xf bank_mask:0xf bound_ctrl:1
	v_mov_b32_e32 v197, v196
	s_nop 1
	v_permlane16_swap_b32_e32 v196, v197
	v_add_f32_e32 v196, v196, v197
	v_pk_fma_f32 v[82:83], v[196:197], v[168:169], v[194:195] op_sel_hi:[0,1,1] neg_lo:[1,0,0] neg_hi:[1,0,0]
	ds_read_b64 v[162:163], v98 offset:32000
	ds_read_b64 v[164:165], v98 offset:23808
	ds_read_b64 v[166:167], v98 offset:15616
	ds_read_b64 v[168:169], v98 offset:40192
	ds_read_b32 v170, v99 offset:1856
	ds_read_b64 v[188:189], v98 offset:7680
	s_waitcnt lgkmcnt(6)
	v_pk_mul_f32 v[190:191], v[82:83], v[174:175]
	v_add_f32_e32 v196, v190, v191
	v_pk_mul_f32 v[192:193], v[82:83], v[186:187]
	v_pk_mul_f32 v[194:195], v[82:83], v[176:177]
	v_add_f32_dpp v196, v196, v196 quad_perm:[1,0,3,2] row_mask:0xf bank_mask:0xf bound_ctrl:1
	v_add_f32_e32 v198, v192, v193
	v_pk_fma_f32 v[194:195], v[182:183], v[178:179], v[194:195] op_sel_hi:[0,1,1]
	v_add_f32_dpp v196, v196, v196 quad_perm:[2,3,0,1] row_mask:0xf bank_mask:0xf bound_ctrl:1
	v_add_f32_dpp v198, v198, v198 quad_perm:[1,0,3,2] row_mask:0xf bank_mask:0xf bound_ctrl:1
	ds_write_b32 v100, v198 offset:15872
	v_add_f32_dpp v196, v196, v196 row_half_mirror row_mask:0xf bank_mask:0xf bound_ctrl:1
	s_nop 1
	v_add_f32_dpp v196, v196, v196 row_mirror row_mask:0xf bank_mask:0xf bound_ctrl:1
	v_mov_b32_e32 v197, v196
	s_nop 1
	v_permlane16_swap_b32_e32 v196, v197
	v_add_f32_e32 v196, v196, v197
	v_pk_fma_f32 v[82:83], v[196:197], v[180:181], v[194:195] op_sel_hi:[0,1,1] neg_lo:[1,0,0] neg_hi:[1,0,0]
	ds_read_b64 v[174:175], v98 offset:31744
	ds_read_b64 v[176:177], v98 offset:23552
	ds_read_b64 v[178:179], v98 offset:15360
	ds_read_b64 v[180:181], v98 offset:39936
	ds_read_b32 v182, v99 offset:1792
	ds_read_b64 v[186:187], v98 offset:7424
	s_waitcnt lgkmcnt(7)
	v_pk_mul_f32 v[190:191], v[82:83], v[162:163]
	v_add_f32_e32 v196, v190, v191
	v_pk_mul_f32 v[192:193], v[82:83], v[188:189]
	v_pk_mul_f32 v[194:195], v[82:83], v[164:165]
	v_add_f32_dpp v196, v196, v196 quad_perm:[1,0,3,2] row_mask:0xf bank_mask:0xf bound_ctrl:1
	v_add_f32_e32 v198, v192, v193
	v_pk_fma_f32 v[194:195], v[170:171], v[166:167], v[194:195] op_sel_hi:[0,1,1]
	v_add_f32_dpp v196, v196, v196 quad_perm:[2,3,0,1] row_mask:0xf bank_mask:0xf bound_ctrl:1
	v_add_f32_dpp v198, v198, v198 quad_perm:[1,0,3,2] row_mask:0xf bank_mask:0xf bound_ctrl:1
	ds_write_b32 v100, v198 offset:15360
	v_add_f32_dpp v196, v196, v196 row_half_mirror row_mask:0xf bank_mask:0xf bound_ctrl:1
	s_nop 1
	v_add_f32_dpp v196, v196, v196 row_mirror row_mask:0xf bank_mask:0xf bound_ctrl:1
	v_mov_b32_e32 v197, v196
	s_nop 1
	v_permlane16_swap_b32_e32 v196, v197
	v_add_f32_e32 v196, v196, v197
	v_pk_fma_f32 v[82:83], v[196:197], v[168:169], v[194:195] op_sel_hi:[0,1,1] neg_lo:[1,0,0] neg_hi:[1,0,0]
	ds_read_b64 v[162:163], v98 offset:31488
	ds_read_b64 v[164:165], v98 offset:23296
	ds_read_b64 v[166:167], v98 offset:15104
	ds_read_b64 v[168:169], v98 offset:39680
	ds_read_b32 v170, v99 offset:1728
	ds_read_b64 v[188:189], v98 offset:7168
	s_waitcnt lgkmcnt(7)
	v_pk_mul_f32 v[190:191], v[82:83], v[174:175]
	v_add_f32_e32 v196, v190, v191
	v_pk_mul_f32 v[192:193], v[82:83], v[186:187]
	v_pk_mul_f32 v[194:195], v[82:83], v[176:177]
	v_add_f32_dpp v196, v196, v196 quad_perm:[1,0,3,2] row_mask:0xf bank_mask:0xf bound_ctrl:1
	v_add_f32_e32 v198, v192, v193
	v_pk_fma_f32 v[194:195], v[182:183], v[178:179], v[194:195] op_sel_hi:[0,1,1]
	v_add_f32_dpp v196, v196, v196 quad_perm:[2,3,0,1] row_mask:0xf bank_mask:0xf bound_ctrl:1
	v_add_f32_dpp v198, v198, v198 quad_perm:[1,0,3,2] row_mask:0xf bank_mask:0xf bound_ctrl:1
	ds_write_b32 v100, v198 offset:14848
	v_add_f32_dpp v196, v196, v196 row_half_mirror row_mask:0xf bank_mask:0xf bound_ctrl:1
	s_nop 1
	v_add_f32_dpp v196, v196, v196 row_mirror row_mask:0xf bank_mask:0xf bound_ctrl:1
	v_mov_b32_e32 v197, v196
	s_nop 1
	v_permlane16_swap_b32_e32 v196, v197
	v_add_f32_e32 v196, v196, v197
	v_pk_fma_f32 v[82:83], v[196:197], v[180:181], v[194:195] op_sel_hi:[0,1,1] neg_lo:[1,0,0] neg_hi:[1,0,0]
	ds_read_b64 v[174:175], v98 offset:31232
	ds_read_b64 v[176:177], v98 offset:23040
	ds_read_b64 v[178:179], v98 offset:14848
	ds_read_b64 v[180:181], v98 offset:39424
	ds_read_b32 v182, v99 offset:1664
	ds_read_b64 v[186:187], v98 offset:6912
	s_waitcnt lgkmcnt(7)
	v_pk_mul_f32 v[190:191], v[82:83], v[162:163]
	v_add_f32_e32 v196, v190, v191
	v_pk_mul_f32 v[192:193], v[82:83], v[188:189]
	v_pk_mul_f32 v[194:195], v[82:83], v[164:165]
	v_add_f32_dpp v196, v196, v196 quad_perm:[1,0,3,2] row_mask:0xf bank_mask:0xf bound_ctrl:1
	v_add_f32_e32 v198, v192, v193
	v_pk_fma_f32 v[194:195], v[170:171], v[166:167], v[194:195] op_sel_hi:[0,1,1]
	v_add_f32_dpp v196, v196, v196 quad_perm:[2,3,0,1] row_mask:0xf bank_mask:0xf bound_ctrl:1
	v_add_f32_dpp v198, v198, v198 quad_perm:[1,0,3,2] row_mask:0xf bank_mask:0xf bound_ctrl:1
	ds_write_b32 v100, v198 offset:14336
	v_add_f32_dpp v196, v196, v196 row_half_mirror row_mask:0xf bank_mask:0xf bound_ctrl:1
	s_nop 1
	v_add_f32_dpp v196, v196, v196 row_mirror row_mask:0xf bank_mask:0xf bound_ctrl:1
	v_mov_b32_e32 v197, v196
	s_nop 1
	v_permlane16_swap_b32_e32 v196, v197
	v_add_f32_e32 v196, v196, v197
	v_pk_fma_f32 v[82:83], v[196:197], v[168:169], v[194:195] op_sel_hi:[0,1,1] neg_lo:[1,0,0] neg_hi:[1,0,0]
	ds_read_b64 v[162:163], v98 offset:30976
	ds_read_b64 v[164:165], v98 offset:22784
	ds_read_b64 v[166:167], v98 offset:14592
	ds_read_b64 v[168:169], v98 offset:39168
	ds_read_b32 v170, v99 offset:1600
	ds_read_b64 v[188:189], v98 offset:6656
	s_waitcnt lgkmcnt(7)
	v_pk_mul_f32 v[190:191], v[82:83], v[174:175]
	v_add_f32_e32 v196, v190, v191
	v_pk_mul_f32 v[192:193], v[82:83], v[186:187]
	v_pk_mul_f32 v[194:195], v[82:83], v[176:177]
	v_add_f32_dpp v196, v196, v196 quad_perm:[1,0,3,2] row_mask:0xf bank_mask:0xf bound_ctrl:1
	v_add_f32_e32 v198, v192, v193
	v_pk_fma_f32 v[194:195], v[182:183], v[178:179], v[194:195] op_sel_hi:[0,1,1]
	v_add_f32_dpp v196, v196, v196 quad_perm:[2,3,0,1] row_mask:0xf bank_mask:0xf bound_ctrl:1
	v_add_f32_dpp v198, v198, v198 quad_perm:[1,0,3,2] row_mask:0xf bank_mask:0xf bound_ctrl:1
	ds_write_b32 v100, v198 offset:13824
	v_add_f32_dpp v196, v196, v196 row_half_mirror row_mask:0xf bank_mask:0xf bound_ctrl:1
	s_nop 1
	v_add_f32_dpp v196, v196, v196 row_mirror row_mask:0xf bank_mask:0xf bound_ctrl:1
	v_mov_b32_e32 v197, v196
	s_nop 1
	v_permlane16_swap_b32_e32 v196, v197
	v_add_f32_e32 v196, v196, v197
	v_pk_fma_f32 v[82:83], v[196:197], v[180:181], v[194:195] op_sel_hi:[0,1,1] neg_lo:[1,0,0] neg_hi:[1,0,0]
	ds_read_b64 v[174:175], v98 offset:30720
	ds_read_b64 v[176:177], v98 offset:22528
	ds_read_b64 v[178:179], v98 offset:14336
	ds_read_b64 v[180:181], v98 offset:38912
	ds_read_b32 v182, v99 offset:1536
	ds_read_b64 v[186:187], v98 offset:6400
	s_waitcnt lgkmcnt(7)
	v_pk_mul_f32 v[190:191], v[82:83], v[162:163]
	v_add_f32_e32 v196, v190, v191
	v_pk_mul_f32 v[192:193], v[82:83], v[188:189]
	v_pk_mul_f32 v[194:195], v[82:83], v[164:165]
	v_add_f32_dpp v196, v196, v196 quad_perm:[1,0,3,2] row_mask:0xf bank_mask:0xf bound_ctrl:1
	v_add_f32_e32 v198, v192, v193
	v_pk_fma_f32 v[194:195], v[170:171], v[166:167], v[194:195] op_sel_hi:[0,1,1]
	v_add_f32_dpp v196, v196, v196 quad_perm:[2,3,0,1] row_mask:0xf bank_mask:0xf bound_ctrl:1
	v_add_f32_dpp v198, v198, v198 quad_perm:[1,0,3,2] row_mask:0xf bank_mask:0xf bound_ctrl:1
	ds_write_b32 v100, v198 offset:13312
	v_add_f32_dpp v196, v196, v196 row_half_mirror row_mask:0xf bank_mask:0xf bound_ctrl:1
	s_nop 1
	v_add_f32_dpp v196, v196, v196 row_mirror row_mask:0xf bank_mask:0xf bound_ctrl:1
	v_mov_b32_e32 v197, v196
	s_nop 1
	v_permlane16_swap_b32_e32 v196, v197
	v_add_f32_e32 v196, v196, v197
	v_pk_fma_f32 v[82:83], v[196:197], v[168:169], v[194:195] op_sel_hi:[0,1,1] neg_lo:[1,0,0] neg_hi:[1,0,0]
	ds_read_b64 v[162:163], v98 offset:30464
	ds_read_b64 v[164:165], v98 offset:22272
	ds_read_b64 v[166:167], v98 offset:14080
	ds_read_b64 v[168:169], v98 offset:38656
	ds_read_b32 v170, v99 offset:1472
	ds_read_b64 v[188:189], v98 offset:6144
	s_waitcnt lgkmcnt(7)
	v_pk_mul_f32 v[190:191], v[82:83], v[174:175]
	v_add_f32_e32 v196, v190, v191
	v_pk_mul_f32 v[192:193], v[82:83], v[186:187]
	v_pk_mul_f32 v[194:195], v[82:83], v[176:177]
	v_add_f32_dpp v196, v196, v196 quad_perm:[1,0,3,2] row_mask:0xf bank_mask:0xf bound_ctrl:1
	v_add_f32_e32 v198, v192, v193
	v_pk_fma_f32 v[194:195], v[182:183], v[178:179], v[194:195] op_sel_hi:[0,1,1]
	v_add_f32_dpp v196, v196, v196 quad_perm:[2,3,0,1] row_mask:0xf bank_mask:0xf bound_ctrl:1
	v_add_f32_dpp v198, v198, v198 quad_perm:[1,0,3,2] row_mask:0xf bank_mask:0xf bound_ctrl:1
	ds_write_b32 v100, v198 offset:12800
	v_add_f32_dpp v196, v196, v196 row_half_mirror row_mask:0xf bank_mask:0xf bound_ctrl:1
	s_nop 1
	v_add_f32_dpp v196, v196, v196 row_mirror row_mask:0xf bank_mask:0xf bound_ctrl:1
	v_mov_b32_e32 v197, v196
	s_nop 1
	v_permlane16_swap_b32_e32 v196, v197
	v_add_f32_e32 v196, v196, v197
	v_pk_fma_f32 v[82:83], v[196:197], v[180:181], v[194:195] op_sel_hi:[0,1,1] neg_lo:[1,0,0] neg_hi:[1,0,0]
	ds_read_b64 v[174:175], v98 offset:30208
	ds_read_b64 v[176:177], v98 offset:22016
	ds_read_b64 v[178:179], v98 offset:13824
	ds_read_b64 v[180:181], v98 offset:38400
	ds_read_b32 v182, v99 offset:1408
	ds_read_b64 v[186:187], v98 offset:5888
	s_waitcnt lgkmcnt(7)
	v_pk_mul_f32 v[190:191], v[82:83], v[162:163]
	v_add_f32_e32 v196, v190, v191
	v_pk_mul_f32 v[192:193], v[82:83], v[188:189]
	v_pk_mul_f32 v[194:195], v[82:83], v[164:165]
	v_add_f32_dpp v196, v196, v196 quad_perm:[1,0,3,2] row_mask:0xf bank_mask:0xf bound_ctrl:1
	v_add_f32_e32 v198, v192, v193
	v_pk_fma_f32 v[194:195], v[170:171], v[166:167], v[194:195] op_sel_hi:[0,1,1]
	v_add_f32_dpp v196, v196, v196 quad_perm:[2,3,0,1] row_mask:0xf bank_mask:0xf bound_ctrl:1
	v_add_f32_dpp v198, v198, v198 quad_perm:[1,0,3,2] row_mask:0xf bank_mask:0xf bound_ctrl:1
	ds_write_b32 v100, v198 offset:12288
	v_add_f32_dpp v196, v196, v196 row_half_mirror row_mask:0xf bank_mask:0xf bound_ctrl:1
	s_nop 1
	v_add_f32_dpp v196, v196, v196 row_mirror row_mask:0xf bank_mask:0xf bound_ctrl:1
	v_mov_b32_e32 v197, v196
	s_nop 1
	v_permlane16_swap_b32_e32 v196, v197
	v_add_f32_e32 v196, v196, v197
	v_pk_fma_f32 v[82:83], v[196:197], v[168:169], v[194:195] op_sel_hi:[0,1,1] neg_lo:[1,0,0] neg_hi:[1,0,0]
	ds_read_b64 v[162:163], v98 offset:29952
	ds_read_b64 v[164:165], v98 offset:21760
	ds_read_b64 v[166:167], v98 offset:13568
	ds_read_b64 v[168:169], v98 offset:38144
	ds_read_b32 v170, v99 offset:1344
	ds_read_b64 v[188:189], v98 offset:5632
	s_waitcnt lgkmcnt(7)
	v_pk_mul_f32 v[190:191], v[82:83], v[174:175]
	v_add_f32_e32 v196, v190, v191
	v_pk_mul_f32 v[192:193], v[82:83], v[186:187]
	v_pk_mul_f32 v[194:195], v[82:83], v[176:177]
	v_add_f32_dpp v196, v196, v196 quad_perm:[1,0,3,2] row_mask:0xf bank_mask:0xf bound_ctrl:1
	v_add_f32_e32 v198, v192, v193
	v_pk_fma_f32 v[194:195], v[182:183], v[178:179], v[194:195] op_sel_hi:[0,1,1]
	v_add_f32_dpp v196, v196, v196 quad_perm:[2,3,0,1] row_mask:0xf bank_mask:0xf bound_ctrl:1
	v_add_f32_dpp v198, v198, v198 quad_perm:[1,0,3,2] row_mask:0xf bank_mask:0xf bound_ctrl:1
	ds_write_b32 v100, v198 offset:11776
	v_add_f32_dpp v196, v196, v196 row_half_mirror row_mask:0xf bank_mask:0xf bound_ctrl:1
	s_nop 1
	v_add_f32_dpp v196, v196, v196 row_mirror row_mask:0xf bank_mask:0xf bound_ctrl:1
	v_mov_b32_e32 v197, v196
	s_nop 1
	v_permlane16_swap_b32_e32 v196, v197
	v_add_f32_e32 v196, v196, v197
	v_pk_fma_f32 v[82:83], v[196:197], v[180:181], v[194:195] op_sel_hi:[0,1,1] neg_lo:[1,0,0] neg_hi:[1,0,0]
	ds_read_b64 v[174:175], v98 offset:29696
	ds_read_b64 v[176:177], v98 offset:21504
	ds_read_b64 v[178:179], v98 offset:13312
	ds_read_b64 v[180:181], v98 offset:37888
	ds_read_b32 v182, v99 offset:1280
	ds_read_b64 v[186:187], v98 offset:5376
	s_waitcnt lgkmcnt(7)
	v_pk_mul_f32 v[190:191], v[82:83], v[162:163]
	v_add_f32_e32 v196, v190, v191
	v_pk_mul_f32 v[192:193], v[82:83], v[188:189]
	v_pk_mul_f32 v[194:195], v[82:83], v[164:165]
	v_add_f32_dpp v196, v196, v196 quad_perm:[1,0,3,2] row_mask:0xf bank_mask:0xf bound_ctrl:1
	v_add_f32_e32 v198, v192, v193
	v_pk_fma_f32 v[194:195], v[170:171], v[166:167], v[194:195] op_sel_hi:[0,1,1]
	v_add_f32_dpp v196, v196, v196 quad_perm:[2,3,0,1] row_mask:0xf bank_mask:0xf bound_ctrl:1
	v_add_f32_dpp v198, v198, v198 quad_perm:[1,0,3,2] row_mask:0xf bank_mask:0xf bound_ctrl:1
	ds_write_b32 v100, v198 offset:11264
	v_add_f32_dpp v196, v196, v196 row_half_mirror row_mask:0xf bank_mask:0xf bound_ctrl:1
	s_nop 1
	v_add_f32_dpp v196, v196, v196 row_mirror row_mask:0xf bank_mask:0xf bound_ctrl:1
	v_mov_b32_e32 v197, v196
	s_nop 1
	v_permlane16_swap_b32_e32 v196, v197
	v_add_f32_e32 v196, v196, v197
	v_pk_fma_f32 v[82:83], v[196:197], v[168:169], v[194:195] op_sel_hi:[0,1,1] neg_lo:[1,0,0] neg_hi:[1,0,0]
	ds_read_b64 v[162:163], v98 offset:29440
	ds_read_b64 v[164:165], v98 offset:21248
	ds_read_b64 v[166:167], v98 offset:13056
	ds_read_b64 v[168:169], v98 offset:37632
	ds_read_b32 v170, v99 offset:1216
	ds_read_b64 v[188:189], v98 offset:5120
	s_waitcnt lgkmcnt(7)
	v_pk_mul_f32 v[190:191], v[82:83], v[174:175]
	v_add_f32_e32 v196, v190, v191
	v_pk_mul_f32 v[192:193], v[82:83], v[186:187]
	v_pk_mul_f32 v[194:195], v[82:83], v[176:177]
	v_add_f32_dpp v196, v196, v196 quad_perm:[1,0,3,2] row_mask:0xf bank_mask:0xf bound_ctrl:1
	v_add_f32_e32 v198, v192, v193
	v_pk_fma_f32 v[194:195], v[182:183], v[178:179], v[194:195] op_sel_hi:[0,1,1]
	v_add_f32_dpp v196, v196, v196 quad_perm:[2,3,0,1] row_mask:0xf bank_mask:0xf bound_ctrl:1
	v_add_f32_dpp v198, v198, v198 quad_perm:[1,0,3,2] row_mask:0xf bank_mask:0xf bound_ctrl:1
	ds_write_b32 v100, v198 offset:10752
	v_add_f32_dpp v196, v196, v196 row_half_mirror row_mask:0xf bank_mask:0xf bound_ctrl:1
	s_nop 1
	v_add_f32_dpp v196, v196, v196 row_mirror row_mask:0xf bank_mask:0xf bound_ctrl:1
	v_mov_b32_e32 v197, v196
	s_nop 1
	v_permlane16_swap_b32_e32 v196, v197
	v_add_f32_e32 v196, v196, v197
	v_pk_fma_f32 v[82:83], v[196:197], v[180:181], v[194:195] op_sel_hi:[0,1,1] neg_lo:[1,0,0] neg_hi:[1,0,0]
	ds_read_b64 v[174:175], v98 offset:29184
	ds_read_b64 v[176:177], v98 offset:20992
	ds_read_b64 v[178:179], v98 offset:12800
	ds_read_b64 v[180:181], v98 offset:37376
	ds_read_b32 v182, v99 offset:1152
	ds_read_b64 v[186:187], v98 offset:4864
	s_waitcnt lgkmcnt(7)
	v_pk_mul_f32 v[190:191], v[82:83], v[162:163]
	v_add_f32_e32 v196, v190, v191
	v_pk_mul_f32 v[192:193], v[82:83], v[188:189]
	v_pk_mul_f32 v[194:195], v[82:83], v[164:165]
	v_add_f32_dpp v196, v196, v196 quad_perm:[1,0,3,2] row_mask:0xf bank_mask:0xf bound_ctrl:1
	v_add_f32_e32 v198, v192, v193
	v_pk_fma_f32 v[194:195], v[170:171], v[166:167], v[194:195] op_sel_hi:[0,1,1]
	v_add_f32_dpp v196, v196, v196 quad_perm:[2,3,0,1] row_mask:0xf bank_mask:0xf bound_ctrl:1
	v_add_f32_dpp v198, v198, v198 quad_perm:[1,0,3,2] row_mask:0xf bank_mask:0xf bound_ctrl:1
	ds_write_b32 v100, v198 offset:10240
	v_add_f32_dpp v196, v196, v196 row_half_mirror row_mask:0xf bank_mask:0xf bound_ctrl:1
	s_nop 1
	v_add_f32_dpp v196, v196, v196 row_mirror row_mask:0xf bank_mask:0xf bound_ctrl:1
	v_mov_b32_e32 v197, v196
	s_nop 1
	v_permlane16_swap_b32_e32 v196, v197
	v_add_f32_e32 v196, v196, v197
	v_pk_fma_f32 v[82:83], v[196:197], v[168:169], v[194:195] op_sel_hi:[0,1,1] neg_lo:[1,0,0] neg_hi:[1,0,0]
	ds_read_b64 v[162:163], v98 offset:28928
	ds_read_b64 v[164:165], v98 offset:20736
	ds_read_b64 v[166:167], v98 offset:12544
	ds_read_b64 v[168:169], v98 offset:37120
	ds_read_b32 v170, v99 offset:1088
	ds_read_b64 v[188:189], v98 offset:4608
	s_waitcnt lgkmcnt(7)
	v_pk_mul_f32 v[190:191], v[82:83], v[174:175]
	v_add_f32_e32 v196, v190, v191
	v_pk_mul_f32 v[192:193], v[82:83], v[186:187]
	v_pk_mul_f32 v[194:195], v[82:83], v[176:177]
	v_add_f32_dpp v196, v196, v196 quad_perm:[1,0,3,2] row_mask:0xf bank_mask:0xf bound_ctrl:1
	v_add_f32_e32 v198, v192, v193
	v_pk_fma_f32 v[194:195], v[182:183], v[178:179], v[194:195] op_sel_hi:[0,1,1]
	v_add_f32_dpp v196, v196, v196 quad_perm:[2,3,0,1] row_mask:0xf bank_mask:0xf bound_ctrl:1
	v_add_f32_dpp v198, v198, v198 quad_perm:[1,0,3,2] row_mask:0xf bank_mask:0xf bound_ctrl:1
	ds_write_b32 v100, v198 offset:9728
	v_add_f32_dpp v196, v196, v196 row_half_mirror row_mask:0xf bank_mask:0xf bound_ctrl:1
	s_nop 1
	v_add_f32_dpp v196, v196, v196 row_mirror row_mask:0xf bank_mask:0xf bound_ctrl:1
	v_mov_b32_e32 v197, v196
	s_nop 1
	v_permlane16_swap_b32_e32 v196, v197
	v_add_f32_e32 v196, v196, v197
	v_pk_fma_f32 v[82:83], v[196:197], v[180:181], v[194:195] op_sel_hi:[0,1,1] neg_lo:[1,0,0] neg_hi:[1,0,0]
	ds_read_b64 v[174:175], v98 offset:28672
	ds_read_b64 v[176:177], v98 offset:20480
	ds_read_b64 v[178:179], v98 offset:12288
	ds_read_b64 v[180:181], v98 offset:36864
	ds_read_b32 v182, v99 offset:1024
	ds_read_b64 v[186:187], v98 offset:4352
	s_waitcnt lgkmcnt(7)
	v_pk_mul_f32 v[190:191], v[82:83], v[162:163]
	v_add_f32_e32 v196, v190, v191
	v_pk_mul_f32 v[192:193], v[82:83], v[188:189]
	v_pk_mul_f32 v[194:195], v[82:83], v[164:165]
	v_add_f32_dpp v196, v196, v196 quad_perm:[1,0,3,2] row_mask:0xf bank_mask:0xf bound_ctrl:1
	v_add_f32_e32 v198, v192, v193
	v_pk_fma_f32 v[194:195], v[170:171], v[166:167], v[194:195] op_sel_hi:[0,1,1]
	v_add_f32_dpp v196, v196, v196 quad_perm:[2,3,0,1] row_mask:0xf bank_mask:0xf bound_ctrl:1
	v_add_f32_dpp v198, v198, v198 quad_perm:[1,0,3,2] row_mask:0xf bank_mask:0xf bound_ctrl:1
	ds_write_b32 v100, v198 offset:9216
	v_add_f32_dpp v196, v196, v196 row_half_mirror row_mask:0xf bank_mask:0xf bound_ctrl:1
	s_nop 1
	v_add_f32_dpp v196, v196, v196 row_mirror row_mask:0xf bank_mask:0xf bound_ctrl:1
	v_mov_b32_e32 v197, v196
	s_nop 1
	v_permlane16_swap_b32_e32 v196, v197
	v_add_f32_e32 v196, v196, v197
	v_pk_fma_f32 v[82:83], v[196:197], v[168:169], v[194:195] op_sel_hi:[0,1,1] neg_lo:[1,0,0] neg_hi:[1,0,0]
	ds_read_b64 v[162:163], v98 offset:28416
	ds_read_b64 v[164:165], v98 offset:20224
	ds_read_b64 v[166:167], v98 offset:12032
	ds_read_b64 v[168:169], v98 offset:36608
	ds_read_b32 v170, v99 offset:960
	ds_read_b64 v[188:189], v98 offset:4096
	s_waitcnt lgkmcnt(7)
	v_pk_mul_f32 v[190:191], v[82:83], v[174:175]
	v_add_f32_e32 v196, v190, v191
	v_pk_mul_f32 v[192:193], v[82:83], v[186:187]
	v_pk_mul_f32 v[194:195], v[82:83], v[176:177]
	v_add_f32_dpp v196, v196, v196 quad_perm:[1,0,3,2] row_mask:0xf bank_mask:0xf bound_ctrl:1
	v_add_f32_e32 v198, v192, v193
	v_pk_fma_f32 v[194:195], v[182:183], v[178:179], v[194:195] op_sel_hi:[0,1,1]
	v_add_f32_dpp v196, v196, v196 quad_perm:[2,3,0,1] row_mask:0xf bank_mask:0xf bound_ctrl:1
	v_add_f32_dpp v198, v198, v198 quad_perm:[1,0,3,2] row_mask:0xf bank_mask:0xf bound_ctrl:1
	ds_write_b32 v100, v198 offset:8704
	v_add_f32_dpp v196, v196, v196 row_half_mirror row_mask:0xf bank_mask:0xf bound_ctrl:1
	s_nop 1
	v_add_f32_dpp v196, v196, v196 row_mirror row_mask:0xf bank_mask:0xf bound_ctrl:1
	v_mov_b32_e32 v197, v196
	s_nop 1
	v_permlane16_swap_b32_e32 v196, v197
	v_add_f32_e32 v196, v196, v197
	v_pk_fma_f32 v[82:83], v[196:197], v[180:181], v[194:195] op_sel_hi:[0,1,1] neg_lo:[1,0,0] neg_hi:[1,0,0]
	ds_read_b64 v[174:175], v98 offset:28160
	ds_read_b64 v[176:177], v98 offset:19968
	ds_read_b64 v[178:179], v98 offset:11776
	ds_read_b64 v[180:181], v98 offset:36352
	ds_read_b32 v182, v99 offset:896
	ds_read_b64 v[186:187], v98 offset:3840
	s_waitcnt lgkmcnt(7)
	v_pk_mul_f32 v[190:191], v[82:83], v[162:163]
	v_add_f32_e32 v196, v190, v191
	v_pk_mul_f32 v[192:193], v[82:83], v[188:189]
	v_pk_mul_f32 v[194:195], v[82:83], v[164:165]
	v_add_f32_dpp v196, v196, v196 quad_perm:[1,0,3,2] row_mask:0xf bank_mask:0xf bound_ctrl:1
	v_add_f32_e32 v198, v192, v193
	v_pk_fma_f32 v[194:195], v[170:171], v[166:167], v[194:195] op_sel_hi:[0,1,1]
	v_add_f32_dpp v196, v196, v196 quad_perm:[2,3,0,1] row_mask:0xf bank_mask:0xf bound_ctrl:1
	v_add_f32_dpp v198, v198, v198 quad_perm:[1,0,3,2] row_mask:0xf bank_mask:0xf bound_ctrl:1
	ds_write_b32 v100, v198 offset:8192
	v_add_f32_dpp v196, v196, v196 row_half_mirror row_mask:0xf bank_mask:0xf bound_ctrl:1
	s_nop 1
	v_add_f32_dpp v196, v196, v196 row_mirror row_mask:0xf bank_mask:0xf bound_ctrl:1
	v_mov_b32_e32 v197, v196
	s_nop 1
	v_permlane16_swap_b32_e32 v196, v197
	v_add_f32_e32 v196, v196, v197
	v_pk_fma_f32 v[82:83], v[196:197], v[168:169], v[194:195] op_sel_hi:[0,1,1] neg_lo:[1,0,0] neg_hi:[1,0,0]
	ds_read_b64 v[162:163], v98 offset:27904
	ds_read_b64 v[164:165], v98 offset:19712
	ds_read_b64 v[166:167], v98 offset:11520
	ds_read_b64 v[168:169], v98 offset:36096
	ds_read_b32 v170, v99 offset:832
	ds_read_b64 v[188:189], v98 offset:3584
	s_waitcnt lgkmcnt(7)
	v_pk_mul_f32 v[190:191], v[82:83], v[174:175]
	v_add_f32_e32 v196, v190, v191
	v_pk_mul_f32 v[192:193], v[82:83], v[186:187]
	v_pk_mul_f32 v[194:195], v[82:83], v[176:177]
	v_add_f32_dpp v196, v196, v196 quad_perm:[1,0,3,2] row_mask:0xf bank_mask:0xf bound_ctrl:1
	v_add_f32_e32 v198, v192, v193
	v_pk_fma_f32 v[194:195], v[182:183], v[178:179], v[194:195] op_sel_hi:[0,1,1]
	v_add_f32_dpp v196, v196, v196 quad_perm:[2,3,0,1] row_mask:0xf bank_mask:0xf bound_ctrl:1
	v_add_f32_dpp v198, v198, v198 quad_perm:[1,0,3,2] row_mask:0xf bank_mask:0xf bound_ctrl:1
	ds_write_b32 v100, v198 offset:7680
	v_add_f32_dpp v196, v196, v196 row_half_mirror row_mask:0xf bank_mask:0xf bound_ctrl:1
	s_nop 1
	v_add_f32_dpp v196, v196, v196 row_mirror row_mask:0xf bank_mask:0xf bound_ctrl:1
	v_mov_b32_e32 v197, v196
	s_nop 1
	v_permlane16_swap_b32_e32 v196, v197
	v_add_f32_e32 v196, v196, v197
	v_pk_fma_f32 v[82:83], v[196:197], v[180:181], v[194:195] op_sel_hi:[0,1,1] neg_lo:[1,0,0] neg_hi:[1,0,0]
	ds_read_b64 v[174:175], v98 offset:27648
	ds_read_b64 v[176:177], v98 offset:19456
	ds_read_b64 v[178:179], v98 offset:11264
	ds_read_b64 v[180:181], v98 offset:35840
	ds_read_b32 v182, v99 offset:768
	ds_read_b64 v[186:187], v98 offset:3328
	s_waitcnt lgkmcnt(7)
	v_pk_mul_f32 v[190:191], v[82:83], v[162:163]
	v_add_f32_e32 v196, v190, v191
	v_pk_mul_f32 v[192:193], v[82:83], v[188:189]
	v_pk_mul_f32 v[194:195], v[82:83], v[164:165]
	v_add_f32_dpp v196, v196, v196 quad_perm:[1,0,3,2] row_mask:0xf bank_mask:0xf bound_ctrl:1
	v_add_f32_e32 v198, v192, v193
	v_pk_fma_f32 v[194:195], v[170:171], v[166:167], v[194:195] op_sel_hi:[0,1,1]
	v_add_f32_dpp v196, v196, v196 quad_perm:[2,3,0,1] row_mask:0xf bank_mask:0xf bound_ctrl:1
	v_add_f32_dpp v198, v198, v198 quad_perm:[1,0,3,2] row_mask:0xf bank_mask:0xf bound_ctrl:1
	ds_write_b32 v100, v198 offset:7168
	v_add_f32_dpp v196, v196, v196 row_half_mirror row_mask:0xf bank_mask:0xf bound_ctrl:1
	s_nop 1
	v_add_f32_dpp v196, v196, v196 row_mirror row_mask:0xf bank_mask:0xf bound_ctrl:1
	v_mov_b32_e32 v197, v196
	s_nop 1
	v_permlane16_swap_b32_e32 v196, v197
	v_add_f32_e32 v196, v196, v197
	v_pk_fma_f32 v[82:83], v[196:197], v[168:169], v[194:195] op_sel_hi:[0,1,1] neg_lo:[1,0,0] neg_hi:[1,0,0]
	ds_read_b64 v[162:163], v98 offset:27392
	ds_read_b64 v[164:165], v98 offset:19200
	ds_read_b64 v[166:167], v98 offset:11008
	ds_read_b64 v[168:169], v98 offset:35584
	ds_read_b32 v170, v99 offset:704
	ds_read_b64 v[188:189], v98 offset:3072
	s_waitcnt lgkmcnt(7)
	v_pk_mul_f32 v[190:191], v[82:83], v[174:175]
	v_add_f32_e32 v196, v190, v191
	v_pk_mul_f32 v[192:193], v[82:83], v[186:187]
	v_pk_mul_f32 v[194:195], v[82:83], v[176:177]
	v_add_f32_dpp v196, v196, v196 quad_perm:[1,0,3,2] row_mask:0xf bank_mask:0xf bound_ctrl:1
	v_add_f32_e32 v198, v192, v193
	v_pk_fma_f32 v[194:195], v[182:183], v[178:179], v[194:195] op_sel_hi:[0,1,1]
	v_add_f32_dpp v196, v196, v196 quad_perm:[2,3,0,1] row_mask:0xf bank_mask:0xf bound_ctrl:1
	v_add_f32_dpp v198, v198, v198 quad_perm:[1,0,3,2] row_mask:0xf bank_mask:0xf bound_ctrl:1
	ds_write_b32 v100, v198 offset:6656
	v_add_f32_dpp v196, v196, v196 row_half_mirror row_mask:0xf bank_mask:0xf bound_ctrl:1
	s_nop 1
	v_add_f32_dpp v196, v196, v196 row_mirror row_mask:0xf bank_mask:0xf bound_ctrl:1
	v_mov_b32_e32 v197, v196
	s_nop 1
	v_permlane16_swap_b32_e32 v196, v197
	v_add_f32_e32 v196, v196, v197
	v_pk_fma_f32 v[82:83], v[196:197], v[180:181], v[194:195] op_sel_hi:[0,1,1] neg_lo:[1,0,0] neg_hi:[1,0,0]
	ds_read_b64 v[174:175], v98 offset:27136
	ds_read_b64 v[176:177], v98 offset:18944
	ds_read_b64 v[178:179], v98 offset:10752
	ds_read_b64 v[180:181], v98 offset:35328
	ds_read_b32 v182, v99 offset:640
	ds_read_b64 v[186:187], v98 offset:2816
	s_waitcnt lgkmcnt(7)
	v_pk_mul_f32 v[190:191], v[82:83], v[162:163]
	v_add_f32_e32 v196, v190, v191
	v_pk_mul_f32 v[192:193], v[82:83], v[188:189]
	v_pk_mul_f32 v[194:195], v[82:83], v[164:165]
	v_add_f32_dpp v196, v196, v196 quad_perm:[1,0,3,2] row_mask:0xf bank_mask:0xf bound_ctrl:1
	v_add_f32_e32 v198, v192, v193
	v_pk_fma_f32 v[194:195], v[170:171], v[166:167], v[194:195] op_sel_hi:[0,1,1]
	v_add_f32_dpp v196, v196, v196 quad_perm:[2,3,0,1] row_mask:0xf bank_mask:0xf bound_ctrl:1
	v_add_f32_dpp v198, v198, v198 quad_perm:[1,0,3,2] row_mask:0xf bank_mask:0xf bound_ctrl:1
	ds_write_b32 v100, v198 offset:6144
	v_add_f32_dpp v196, v196, v196 row_half_mirror row_mask:0xf bank_mask:0xf bound_ctrl:1
	s_nop 1
	v_add_f32_dpp v196, v196, v196 row_mirror row_mask:0xf bank_mask:0xf bound_ctrl:1
	v_mov_b32_e32 v197, v196
	s_nop 1
	v_permlane16_swap_b32_e32 v196, v197
	v_add_f32_e32 v196, v196, v197
	v_pk_fma_f32 v[82:83], v[196:197], v[168:169], v[194:195] op_sel_hi:[0,1,1] neg_lo:[1,0,0] neg_hi:[1,0,0]
	ds_read_b64 v[162:163], v98 offset:26880
	ds_read_b64 v[164:165], v98 offset:18688
	ds_read_b64 v[166:167], v98 offset:10496
	ds_read_b64 v[168:169], v98 offset:35072
	ds_read_b32 v170, v99 offset:576
	ds_read_b64 v[188:189], v98 offset:2560
	s_waitcnt lgkmcnt(7)
	v_pk_mul_f32 v[190:191], v[82:83], v[174:175]
	v_add_f32_e32 v196, v190, v191
	v_pk_mul_f32 v[192:193], v[82:83], v[186:187]
	v_pk_mul_f32 v[194:195], v[82:83], v[176:177]
	v_add_f32_dpp v196, v196, v196 quad_perm:[1,0,3,2] row_mask:0xf bank_mask:0xf bound_ctrl:1
	v_add_f32_e32 v198, v192, v193
	v_pk_fma_f32 v[194:195], v[182:183], v[178:179], v[194:195] op_sel_hi:[0,1,1]
	v_add_f32_dpp v196, v196, v196 quad_perm:[2,3,0,1] row_mask:0xf bank_mask:0xf bound_ctrl:1
	v_add_f32_dpp v198, v198, v198 quad_perm:[1,0,3,2] row_mask:0xf bank_mask:0xf bound_ctrl:1
	ds_write_b32 v100, v198 offset:5632
	v_add_f32_dpp v196, v196, v196 row_half_mirror row_mask:0xf bank_mask:0xf bound_ctrl:1
	s_nop 1
	v_add_f32_dpp v196, v196, v196 row_mirror row_mask:0xf bank_mask:0xf bound_ctrl:1
	v_mov_b32_e32 v197, v196
	s_nop 1
	v_permlane16_swap_b32_e32 v196, v197
	v_add_f32_e32 v196, v196, v197
	v_pk_fma_f32 v[82:83], v[196:197], v[180:181], v[194:195] op_sel_hi:[0,1,1] neg_lo:[1,0,0] neg_hi:[1,0,0]
	ds_read_b64 v[174:175], v98 offset:26624
	ds_read_b64 v[176:177], v98 offset:18432
	ds_read_b64 v[178:179], v98 offset:10240
	ds_read_b64 v[180:181], v98 offset:34816
	ds_read_b32 v182, v99 offset:512
	ds_read_b64 v[186:187], v98 offset:2304
	s_waitcnt lgkmcnt(7)
	v_pk_mul_f32 v[190:191], v[82:83], v[162:163]
	v_add_f32_e32 v196, v190, v191
	v_pk_mul_f32 v[192:193], v[82:83], v[188:189]
	v_pk_mul_f32 v[194:195], v[82:83], v[164:165]
	v_add_f32_dpp v196, v196, v196 quad_perm:[1,0,3,2] row_mask:0xf bank_mask:0xf bound_ctrl:1
	v_add_f32_e32 v198, v192, v193
	v_pk_fma_f32 v[194:195], v[170:171], v[166:167], v[194:195] op_sel_hi:[0,1,1]
	v_add_f32_dpp v196, v196, v196 quad_perm:[2,3,0,1] row_mask:0xf bank_mask:0xf bound_ctrl:1
	v_add_f32_dpp v198, v198, v198 quad_perm:[1,0,3,2] row_mask:0xf bank_mask:0xf bound_ctrl:1
	ds_write_b32 v100, v198 offset:5120
	v_add_f32_dpp v196, v196, v196 row_half_mirror row_mask:0xf bank_mask:0xf bound_ctrl:1
	s_nop 1
	v_add_f32_dpp v196, v196, v196 row_mirror row_mask:0xf bank_mask:0xf bound_ctrl:1
	v_mov_b32_e32 v197, v196
	s_nop 1
	v_permlane16_swap_b32_e32 v196, v197
	v_add_f32_e32 v196, v196, v197
	v_pk_fma_f32 v[82:83], v[196:197], v[168:169], v[194:195] op_sel_hi:[0,1,1] neg_lo:[1,0,0] neg_hi:[1,0,0]
	ds_read_b64 v[162:163], v98 offset:26368
	ds_read_b64 v[164:165], v98 offset:18176
	ds_read_b64 v[166:167], v98 offset:9984
	ds_read_b64 v[168:169], v98 offset:34560
	ds_read_b32 v170, v99 offset:448
	ds_read_b64 v[188:189], v98 offset:2048
	s_waitcnt lgkmcnt(7)
	v_pk_mul_f32 v[190:191], v[82:83], v[174:175]
	v_add_f32_e32 v196, v190, v191
	v_pk_mul_f32 v[192:193], v[82:83], v[186:187]
	v_pk_mul_f32 v[194:195], v[82:83], v[176:177]
	v_add_f32_dpp v196, v196, v196 quad_perm:[1,0,3,2] row_mask:0xf bank_mask:0xf bound_ctrl:1
	v_add_f32_e32 v198, v192, v193
	v_pk_fma_f32 v[194:195], v[182:183], v[178:179], v[194:195] op_sel_hi:[0,1,1]
	v_add_f32_dpp v196, v196, v196 quad_perm:[2,3,0,1] row_mask:0xf bank_mask:0xf bound_ctrl:1
	v_add_f32_dpp v198, v198, v198 quad_perm:[1,0,3,2] row_mask:0xf bank_mask:0xf bound_ctrl:1
	ds_write_b32 v100, v198 offset:4608
	v_add_f32_dpp v196, v196, v196 row_half_mirror row_mask:0xf bank_mask:0xf bound_ctrl:1
	s_nop 1
	v_add_f32_dpp v196, v196, v196 row_mirror row_mask:0xf bank_mask:0xf bound_ctrl:1
	v_mov_b32_e32 v197, v196
	s_nop 1
	v_permlane16_swap_b32_e32 v196, v197
	v_add_f32_e32 v196, v196, v197
	v_pk_fma_f32 v[82:83], v[196:197], v[180:181], v[194:195] op_sel_hi:[0,1,1] neg_lo:[1,0,0] neg_hi:[1,0,0]
	ds_read_b64 v[174:175], v98 offset:26112
	ds_read_b64 v[176:177], v98 offset:17920
	ds_read_b64 v[178:179], v98 offset:9728
	ds_read_b64 v[180:181], v98 offset:34304
	ds_read_b32 v182, v99 offset:384
	ds_read_b64 v[186:187], v98 offset:1792
	s_waitcnt lgkmcnt(7)
	v_pk_mul_f32 v[190:191], v[82:83], v[162:163]
	v_add_f32_e32 v196, v190, v191
	v_pk_mul_f32 v[192:193], v[82:83], v[188:189]
	v_pk_mul_f32 v[194:195], v[82:83], v[164:165]
	v_add_f32_dpp v196, v196, v196 quad_perm:[1,0,3,2] row_mask:0xf bank_mask:0xf bound_ctrl:1
	v_add_f32_e32 v198, v192, v193
	v_pk_fma_f32 v[194:195], v[170:171], v[166:167], v[194:195] op_sel_hi:[0,1,1]
	v_add_f32_dpp v196, v196, v196 quad_perm:[2,3,0,1] row_mask:0xf bank_mask:0xf bound_ctrl:1
	v_add_f32_dpp v198, v198, v198 quad_perm:[1,0,3,2] row_mask:0xf bank_mask:0xf bound_ctrl:1
	ds_write_b32 v100, v198 offset:4096
	v_add_f32_dpp v196, v196, v196 row_half_mirror row_mask:0xf bank_mask:0xf bound_ctrl:1
	s_nop 1
	v_add_f32_dpp v196, v196, v196 row_mirror row_mask:0xf bank_mask:0xf bound_ctrl:1
	v_mov_b32_e32 v197, v196
	s_nop 1
	v_permlane16_swap_b32_e32 v196, v197
	v_add_f32_e32 v196, v196, v197
	v_pk_fma_f32 v[82:83], v[196:197], v[168:169], v[194:195] op_sel_hi:[0,1,1] neg_lo:[1,0,0] neg_hi:[1,0,0]
	ds_read_b64 v[162:163], v98 offset:25856
	ds_read_b64 v[164:165], v98 offset:17664
	ds_read_b64 v[166:167], v98 offset:9472
	ds_read_b64 v[168:169], v98 offset:34048
	ds_read_b32 v170, v99 offset:320
	ds_read_b64 v[188:189], v98 offset:1536
	s_waitcnt lgkmcnt(7)
	v_pk_mul_f32 v[190:191], v[82:83], v[174:175]
	v_add_f32_e32 v196, v190, v191
	v_pk_mul_f32 v[192:193], v[82:83], v[186:187]
	v_pk_mul_f32 v[194:195], v[82:83], v[176:177]
	v_add_f32_dpp v196, v196, v196 quad_perm:[1,0,3,2] row_mask:0xf bank_mask:0xf bound_ctrl:1
	v_add_f32_e32 v198, v192, v193
	v_pk_fma_f32 v[194:195], v[182:183], v[178:179], v[194:195] op_sel_hi:[0,1,1]
	v_add_f32_dpp v196, v196, v196 quad_perm:[2,3,0,1] row_mask:0xf bank_mask:0xf bound_ctrl:1
	v_add_f32_dpp v198, v198, v198 quad_perm:[1,0,3,2] row_mask:0xf bank_mask:0xf bound_ctrl:1
	ds_write_b32 v100, v198 offset:3584
	v_add_f32_dpp v196, v196, v196 row_half_mirror row_mask:0xf bank_mask:0xf bound_ctrl:1
	s_nop 1
	v_add_f32_dpp v196, v196, v196 row_mirror row_mask:0xf bank_mask:0xf bound_ctrl:1
	v_mov_b32_e32 v197, v196
	s_nop 1
	v_permlane16_swap_b32_e32 v196, v197
	v_add_f32_e32 v196, v196, v197
	v_pk_fma_f32 v[82:83], v[196:197], v[180:181], v[194:195] op_sel_hi:[0,1,1] neg_lo:[1,0,0] neg_hi:[1,0,0]
	ds_read_b64 v[174:175], v98 offset:25600
	ds_read_b64 v[176:177], v98 offset:17408
	ds_read_b64 v[178:179], v98 offset:9216
	ds_read_b64 v[180:181], v98 offset:33792
	ds_read_b32 v182, v99 offset:256
	ds_read_b64 v[186:187], v98 offset:1280
	s_waitcnt lgkmcnt(7)
	v_pk_mul_f32 v[190:191], v[82:83], v[162:163]
	v_add_f32_e32 v196, v190, v191
	v_pk_mul_f32 v[192:193], v[82:83], v[188:189]
	v_pk_mul_f32 v[194:195], v[82:83], v[164:165]
	v_add_f32_dpp v196, v196, v196 quad_perm:[1,0,3,2] row_mask:0xf bank_mask:0xf bound_ctrl:1
	v_add_f32_e32 v198, v192, v193
	v_pk_fma_f32 v[194:195], v[170:171], v[166:167], v[194:195] op_sel_hi:[0,1,1]
	v_add_f32_dpp v196, v196, v196 quad_perm:[2,3,0,1] row_mask:0xf bank_mask:0xf bound_ctrl:1
	v_add_f32_dpp v198, v198, v198 quad_perm:[1,0,3,2] row_mask:0xf bank_mask:0xf bound_ctrl:1
	ds_write_b32 v100, v198 offset:3072
	v_add_f32_dpp v196, v196, v196 row_half_mirror row_mask:0xf bank_mask:0xf bound_ctrl:1
	s_nop 1
	v_add_f32_dpp v196, v196, v196 row_mirror row_mask:0xf bank_mask:0xf bound_ctrl:1
	v_mov_b32_e32 v197, v196
	s_nop 1
	v_permlane16_swap_b32_e32 v196, v197
	v_add_f32_e32 v196, v196, v197
	v_pk_fma_f32 v[82:83], v[196:197], v[168:169], v[194:195] op_sel_hi:[0,1,1] neg_lo:[1,0,0] neg_hi:[1,0,0]
	ds_read_b64 v[162:163], v98 offset:25344
	ds_read_b64 v[164:165], v98 offset:17152
	ds_read_b64 v[166:167], v98 offset:8960
	ds_read_b64 v[168:169], v98 offset:33536
	ds_read_b32 v170, v99 offset:192
	ds_read_b64 v[188:189], v98 offset:1024
	s_waitcnt lgkmcnt(7)
	v_pk_mul_f32 v[190:191], v[82:83], v[174:175]
	v_add_f32_e32 v196, v190, v191
	v_pk_mul_f32 v[192:193], v[82:83], v[186:187]
	v_pk_mul_f32 v[194:195], v[82:83], v[176:177]
	v_add_f32_dpp v196, v196, v196 quad_perm:[1,0,3,2] row_mask:0xf bank_mask:0xf bound_ctrl:1
	v_add_f32_e32 v198, v192, v193
	v_pk_fma_f32 v[194:195], v[182:183], v[178:179], v[194:195] op_sel_hi:[0,1,1]
	v_add_f32_dpp v196, v196, v196 quad_perm:[2,3,0,1] row_mask:0xf bank_mask:0xf bound_ctrl:1
	v_add_f32_dpp v198, v198, v198 quad_perm:[1,0,3,2] row_mask:0xf bank_mask:0xf bound_ctrl:1
	ds_write_b32 v100, v198 offset:2560
	v_add_f32_dpp v196, v196, v196 row_half_mirror row_mask:0xf bank_mask:0xf bound_ctrl:1
	s_nop 1
	v_add_f32_dpp v196, v196, v196 row_mirror row_mask:0xf bank_mask:0xf bound_ctrl:1
	v_mov_b32_e32 v197, v196
	s_nop 1
	v_permlane16_swap_b32_e32 v196, v197
	v_add_f32_e32 v196, v196, v197
	v_pk_fma_f32 v[82:83], v[196:197], v[180:181], v[194:195] op_sel_hi:[0,1,1] neg_lo:[1,0,0] neg_hi:[1,0,0]
	ds_read_b64 v[174:175], v98 offset:25088
	ds_read_b64 v[176:177], v98 offset:16896
	ds_read_b64 v[178:179], v98 offset:8704
	ds_read_b64 v[180:181], v98 offset:33280
	ds_read_b32 v182, v99 offset:128
	ds_read_b64 v[186:187], v98 offset:768
	s_waitcnt lgkmcnt(7)
	v_pk_mul_f32 v[190:191], v[82:83], v[162:163]
	v_add_f32_e32 v196, v190, v191
	v_pk_mul_f32 v[192:193], v[82:83], v[188:189]
	v_pk_mul_f32 v[194:195], v[82:83], v[164:165]
	v_add_f32_dpp v196, v196, v196 quad_perm:[1,0,3,2] row_mask:0xf bank_mask:0xf bound_ctrl:1
	v_add_f32_e32 v198, v192, v193
	v_pk_fma_f32 v[194:195], v[170:171], v[166:167], v[194:195] op_sel_hi:[0,1,1]
	v_add_f32_dpp v196, v196, v196 quad_perm:[2,3,0,1] row_mask:0xf bank_mask:0xf bound_ctrl:1
	v_add_f32_dpp v198, v198, v198 quad_perm:[1,0,3,2] row_mask:0xf bank_mask:0xf bound_ctrl:1
	ds_write_b32 v100, v198 offset:2048
	v_add_f32_dpp v196, v196, v196 row_half_mirror row_mask:0xf bank_mask:0xf bound_ctrl:1
	s_nop 1
	v_add_f32_dpp v196, v196, v196 row_mirror row_mask:0xf bank_mask:0xf bound_ctrl:1
	v_mov_b32_e32 v197, v196
	s_nop 1
	v_permlane16_swap_b32_e32 v196, v197
	v_add_f32_e32 v196, v196, v197
	v_pk_fma_f32 v[82:83], v[196:197], v[168:169], v[194:195] op_sel_hi:[0,1,1] neg_lo:[1,0,0] neg_hi:[1,0,0]
	ds_read_b64 v[162:163], v98 offset:24832
	ds_read_b64 v[164:165], v98 offset:16640
	ds_read_b64 v[166:167], v98 offset:8448
	ds_read_b64 v[168:169], v98 offset:33024
	ds_read_b32 v170, v99 offset:64
	ds_read_b64 v[188:189], v98 offset:512
	s_waitcnt lgkmcnt(7)
	v_pk_mul_f32 v[190:191], v[82:83], v[174:175]
	v_add_f32_e32 v196, v190, v191
	v_pk_mul_f32 v[192:193], v[82:83], v[186:187]
	v_pk_mul_f32 v[194:195], v[82:83], v[176:177]
	v_add_f32_dpp v196, v196, v196 quad_perm:[1,0,3,2] row_mask:0xf bank_mask:0xf bound_ctrl:1
	v_add_f32_e32 v198, v192, v193
	v_pk_fma_f32 v[194:195], v[182:183], v[178:179], v[194:195] op_sel_hi:[0,1,1]
	v_add_f32_dpp v196, v196, v196 quad_perm:[2,3,0,1] row_mask:0xf bank_mask:0xf bound_ctrl:1
	v_add_f32_dpp v198, v198, v198 quad_perm:[1,0,3,2] row_mask:0xf bank_mask:0xf bound_ctrl:1
	ds_write_b32 v100, v198 offset:1536
	v_add_f32_dpp v196, v196, v196 row_half_mirror row_mask:0xf bank_mask:0xf bound_ctrl:1
	s_nop 1
	v_add_f32_dpp v196, v196, v196 row_mirror row_mask:0xf bank_mask:0xf bound_ctrl:1
	v_mov_b32_e32 v197, v196
	s_nop 1
	v_permlane16_swap_b32_e32 v196, v197
	v_add_f32_e32 v196, v196, v197
	v_pk_fma_f32 v[82:83], v[196:197], v[180:181], v[194:195] op_sel_hi:[0,1,1] neg_lo:[1,0,0] neg_hi:[1,0,0]
	ds_read_b64 v[174:175], v98 offset:24576
	ds_read_b64 v[176:177], v98 offset:16384
	ds_read_b64 v[178:179], v98 offset:8192
	ds_read_b64 v[180:181], v98 offset:32768
	ds_read_b32 v182, v99
	ds_read_b64 v[186:187], v98 offset:256
	s_waitcnt lgkmcnt(7)
	v_pk_mul_f32 v[190:191], v[82:83], v[162:163]
	v_add_f32_e32 v196, v190, v191
	v_pk_mul_f32 v[192:193], v[82:83], v[188:189]
	v_pk_mul_f32 v[194:195], v[82:83], v[164:165]
	v_add_f32_dpp v196, v196, v196 quad_perm:[1,0,3,2] row_mask:0xf bank_mask:0xf bound_ctrl:1
	v_add_f32_e32 v198, v192, v193
	v_pk_fma_f32 v[194:195], v[170:171], v[166:167], v[194:195] op_sel_hi:[0,1,1]
	v_add_f32_dpp v196, v196, v196 quad_perm:[2,3,0,1] row_mask:0xf bank_mask:0xf bound_ctrl:1
	v_add_f32_dpp v198, v198, v198 quad_perm:[1,0,3,2] row_mask:0xf bank_mask:0xf bound_ctrl:1
	ds_write_b32 v100, v198 offset:1024
	v_add_f32_dpp v196, v196, v196 row_half_mirror row_mask:0xf bank_mask:0xf bound_ctrl:1
	s_nop 1
	v_add_f32_dpp v196, v196, v196 row_mirror row_mask:0xf bank_mask:0xf bound_ctrl:1
	v_mov_b32_e32 v197, v196
	s_nop 1
	v_permlane16_swap_b32_e32 v196, v197
	v_add_f32_e32 v196, v196, v197
	v_pk_fma_f32 v[82:83], v[196:197], v[168:169], v[194:195] op_sel_hi:[0,1,1] neg_lo:[1,0,0] neg_hi:[1,0,0]
	ds_read_b64 v[188:189], v98
	s_waitcnt lgkmcnt(2)
	v_pk_mul_f32 v[190:191], v[82:83], v[174:175]
	v_add_f32_e32 v196, v190, v191
	v_pk_mul_f32 v[192:193], v[82:83], v[186:187]
	v_pk_mul_f32 v[194:195], v[82:83], v[176:177]
	v_add_f32_dpp v196, v196, v196 quad_perm:[1,0,3,2] row_mask:0xf bank_mask:0xf bound_ctrl:1
	v_add_f32_e32 v198, v192, v193
	v_pk_fma_f32 v[194:195], v[182:183], v[178:179], v[194:195] op_sel_hi:[0,1,1]
	v_add_f32_dpp v196, v196, v196 quad_perm:[2,3,0,1] row_mask:0xf bank_mask:0xf bound_ctrl:1
	v_add_f32_dpp v198, v198, v198 quad_perm:[1,0,3,2] row_mask:0xf bank_mask:0xf bound_ctrl:1
	ds_write_b32 v100, v198 offset:512
	v_add_f32_dpp v196, v196, v196 row_half_mirror row_mask:0xf bank_mask:0xf bound_ctrl:1
	s_nop 1
	v_add_f32_dpp v196, v196, v196 row_mirror row_mask:0xf bank_mask:0xf bound_ctrl:1
	v_mov_b32_e32 v197, v196
	s_nop 1
	v_permlane16_swap_b32_e32 v196, v197
	v_add_f32_e32 v196, v196, v197
	v_pk_fma_f32 v[82:83], v[196:197], v[180:181], v[194:195] op_sel_hi:[0,1,1] neg_lo:[1,0,0] neg_hi:[1,0,0]
	s_waitcnt lgkmcnt(1)
	v_pk_mul_f32 v[192:193], v[82:83], v[188:189]
	v_add_f32_e32 v198, v192, v193
	s_nop 1
	v_add_f32_dpp v198, v198, v198 quad_perm:[1,0,3,2] row_mask:0xf bank_mask:0xf bound_ctrl:1
	ds_write_b32 v100, v198
	s_branch .Lrs_post
.Lrs_fwd:
	ds_read_b64 v[162:163], v98 offset:24576
	ds_read_b64 v[164:165], v98 offset:16384
	ds_read_b64 v[166:167], v98 offset:8192
	ds_read_b64 v[168:169], v98 offset:32768
	ds_read_b32 v170, v99
	ds_read_b64 v[174:175], v98 offset:24832
	ds_read_b64 v[176:177], v98 offset:16640
	ds_read_b64 v[178:179], v98 offset:8448
	ds_read_b64 v[180:181], v98 offset:33024
	ds_read_b32 v182, v99 offset:64
	ds_read_b64 v[186:187], v98
	s_waitcnt lgkmcnt(6)
	v_pk_mul_f32 v[190:191], v[82:83], v[162:163]
	v_add_f32_e32 v196, v190, v191
	v_pk_mul_f32 v[194:195], v[82:83], v[164:165]
	s_nop 0
	v_add_f32_dpp v196, v196, v196 quad_perm:[1,0,3,2] row_mask:0xf bank_mask:0xf bound_ctrl:1
	v_pk_fma_f32 v[194:195], v[170:171], v[166:167], v[194:195] op_sel_hi:[0,1,1]
	s_nop 0
	v_add_f32_dpp v196, v196, v196 quad_perm:[2,3,0,1] row_mask:0xf bank_mask:0xf bound_ctrl:1
	s_nop 1
	v_add_f32_dpp v196, v196, v196 row_half_mirror row_mask:0xf bank_mask:0xf bound_ctrl:1
	s_nop 1
	v_add_f32_dpp v196, v196, v196 row_mirror row_mask:0xf bank_mask:0xf bound_ctrl:1
	v_mov_b32_e32 v197, v196
	s_nop 1
	v_permlane16_swap_b32_e32 v196, v197
	v_add_f32_e32 v196, v196, v197
	v_pk_fma_f32 v[82:83], v[196:197], v[168:169], v[194:195] op_sel_hi:[0,1,1] neg_lo:[1,0,0] neg_hi:[1,0,0]
	ds_read_b64 v[162:163], v98 offset:25088
	ds_read_b64 v[164:165], v98 offset:16896
	ds_read_b64 v[166:167], v98 offset:8704
	ds_read_b64 v[168:169], v98 offset:33280
	ds_read_b32 v170, v99 offset:128
	ds_read_b64 v[188:189], v98 offset:256
	s_waitcnt lgkmcnt(6)
	v_pk_mul_f32 v[190:191], v[82:83], v[174:175]
	v_add_f32_e32 v196, v190, v191
	v_pk_mul_f32 v[192:193], v[82:83], v[186:187]
	v_pk_mul_f32 v[194:195], v[82:83], v[176:177]
	v_add_f32_dpp v196, v196, v196 quad_perm:[1,0,3,2] row_mask:0xf bank_mask:0xf bound_ctrl:1
	v_add_f32_e32 v198, v192, v193
	v_pk_fma_f32 v[194:195], v[182:183], v[178:179], v[194:195] op_sel_hi:[0,1,1]
	v_add_f32_dpp v196, v196, v196 quad_perm:[2,3,0,1] row_mask:0xf bank_mask:0xf bound_ctrl:1
	v_add_f32_dpp v198, v198, v198 quad_perm:[1,0,3,2] row_mask:0xf bank_mask:0xf bound_ctrl:1
	ds_write_b32 v100, v198
	v_add_f32_dpp v196, v196, v196 row_half_mirror row_mask:0xf bank_mask:0xf bound_ctrl:1
	s_nop 1
	v_add_f32_dpp v196, v196, v196 row_mirror row_mask:0xf bank_mask:0xf bound_ctrl:1
	v_mov_b32_e32 v197, v196
	s_nop 1
	v_permlane16_swap_b32_e32 v196, v197
	v_add_f32_e32 v196, v196, v197
	v_pk_fma_f32 v[82:83], v[196:197], v[180:181], v[194:195] op_sel_hi:[0,1,1] neg_lo:[1,0,0] neg_hi:[1,0,0]
	ds_read_b64 v[174:175], v98 offset:25344
	ds_read_b64 v[176:177], v98 offset:17152
	ds_read_b64 v[178:179], v98 offset:8960
	ds_read_b64 v[180:181], v98 offset:33536
	ds_read_b32 v182, v99 offset:192
	ds_read_b64 v[186:187], v98 offset:512
	s_waitcnt lgkmcnt(7)
	v_pk_mul_f32 v[190:191], v[82:83], v[162:163]
	v_add_f32_e32 v196, v190, v191
	v_pk_mul_f32 v[192:193], v[82:83], v[188:189]
	v_pk_mul_f32 v[194:195], v[82:83], v[164:165]
	v_add_f32_dpp v196, v196, v196 quad_perm:[1,0,3,2] row_mask:0xf bank_mask:0xf bound_ctrl:1
	v_add_f32_e32 v198, v192, v193
	v_pk_fma_f32 v[194:195], v[170:171], v[166:167], v[194:195] op_sel_hi:[0,1,1]
	v_add_f32_dpp v196, v196, v196 quad_perm:[2,3,0,1] row_mask:0xf bank_mask:0xf bound_ctrl:1
	v_add_f32_dpp v198, v198, v198 quad_perm:[1,0,3,2] row_mask:0xf bank_mask:0xf bound_ctrl:1
	ds_write_b32 v100, v198 offset:512
	v_add_f32_dpp v196, v196, v196 row_half_mirror row_mask:0xf bank_mask:0xf bound_ctrl:1
	s_nop 1
	v_add_f32_dpp v196, v196, v196 row_mirror row_mask:0xf bank_mask:0xf bound_ctrl:1
	v_mov_b32_e32 v197, v196
	s_nop 1
	v_permlane16_swap_b32_e32 v196, v197
	v_add_f32_e32 v196, v196, v197
	v_pk_fma_f32 v[82:83], v[196:197], v[168:169], v[194:195] op_sel_hi:[0,1,1] neg_lo:[1,0,0] neg_hi:[1,0,0]
	ds_read_b64 v[162:163], v98 offset:25600
	ds_read_b64 v[164:165], v98 offset:17408
	ds_read_b64 v[166:167], v98 offset:9216
	ds_read_b64 v[168:169], v98 offset:33792
	ds_read_b32 v170, v99 offset:256
	ds_read_b64 v[188:189], v98 offset:768
	s_waitcnt lgkmcnt(7)
	v_pk_mul_f32 v[190:191], v[82:83], v[174:175]
	v_add_f32_e32 v196, v190, v191
	v_pk_mul_f32 v[192:193], v[82:83], v[186:187]
	v_pk_mul_f32 v[194:195], v[82:83], v[176:177]
	v_add_f32_dpp v196, v196, v196 quad_perm:[1,0,3,2] row_mask:0xf bank_mask:0xf bound_ctrl:1
	v_add_f32_e32 v198, v192, v193
	v_pk_fma_f32 v[194:195], v[182:183], v[178:179], v[194:195] op_sel_hi:[0,1,1]
	v_add_f32_dpp v196, v196, v196 quad_perm:[2,3,0,1] row_mask:0xf bank_mask:0xf bound_ctrl:1
	v_add_f32_dpp v198, v198, v198 quad_perm:[1,0,3,2] row_mask:0xf bank_mask:0xf bound_ctrl:1
	ds_write_b32 v100, v198 offset:1024
	v_add_f32_dpp v196, v196, v196 row_half_mirror row_mask:0xf bank_mask:0xf bound_ctrl:1
	s_nop 1
	v_add_f32_dpp v196, v196, v196 row_mirror row_mask:0xf bank_mask:0xf bound_ctrl:1
	v_mov_b32_e32 v197, v196
	s_nop 1
	v_permlane16_swap_b32_e32 v196, v197
	v_add_f32_e32 v196, v196, v197
	v_pk_fma_f32 v[82:83], v[196:197], v[180:181], v[194:195] op_sel_hi:[0,1,1] neg_lo:[1,0,0] neg_hi:[1,0,0]
	ds_read_b64 v[174:175], v98 offset:25856
	ds_read_b64 v[176:177], v98 offset:17664
	ds_read_b64 v[178:179], v98 offset:9472
	ds_read_b64 v[180:181], v98 offset:34048
	ds_read_b32 v182, v99 offset:320
	ds_read_b64 v[186:187], v98 offset:1024
	s_waitcnt lgkmcnt(7)
	v_pk_mul_f32 v[190:191], v[82:83], v[162:163]
	v_add_f32_e32 v196, v190, v191
	v_pk_mul_f32 v[192:193], v[82:83], v[188:189]
	v_pk_mul_f32 v[194:195], v[82:83], v[164:165]
	v_add_f32_dpp v196, v196, v196 quad_perm:[1,0,3,2] row_mask:0xf bank_mask:0xf bound_ctrl:1
	v_add_f32_e32 v198, v192, v193
	v_pk_fma_f32 v[194:195], v[170:171], v[166:167], v[194:195] op_sel_hi:[0,1,1]
	v_add_f32_dpp v196, v196, v196 quad_perm:[2,3,0,1] row_mask:0xf bank_mask:0xf bound_ctrl:1
	v_add_f32_dpp v198, v198, v198 quad_perm:[1,0,3,2] row_mask:0xf bank_mask:0xf bound_ctrl:1
	ds_write_b32 v100, v198 offset:1536
	v_add_f32_dpp v196, v196, v196 row_half_mirror row_mask:0xf bank_mask:0xf bound_ctrl:1
	s_nop 1
	v_add_f32_dpp v196, v196, v196 row_mirror row_mask:0xf bank_mask:0xf bound_ctrl:1
	v_mov_b32_e32 v197, v196
	s_nop 1
	v_permlane16_swap_b32_e32 v196, v197
	v_add_f32_e32 v196, v196, v197
	v_pk_fma_f32 v[82:83], v[196:197], v[168:169], v[194:195] op_sel_hi:[0,1,1] neg_lo:[1,0,0] neg_hi:[1,0,0]
	ds_read_b64 v[162:163], v98 offset:26112
	ds_read_b64 v[164:165], v98 offset:17920
	ds_read_b64 v[166:167], v98 offset:9728
	ds_read_b64 v[168:169], v98 offset:34304
	ds_read_b32 v170, v99 offset:384
	ds_read_b64 v[188:189], v98 offset:1280
	s_waitcnt lgkmcnt(7)
	v_pk_mul_f32 v[190:191], v[82:83], v[174:175]
	v_add_f32_e32 v196, v190, v191
	v_pk_mul_f32 v[192:193], v[82:83], v[186:187]
	v_pk_mul_f32 v[194:195], v[82:83], v[176:177]
	v_add_f32_dpp v196, v196, v196 quad_perm:[1,0,3,2] row_mask:0xf bank_mask:0xf bound_ctrl:1
	v_add_f32_e32 v198, v192, v193
	v_pk_fma_f32 v[194:195], v[182:183], v[178:179], v[194:195] op_sel_hi:[0,1,1]
	v_add_f32_dpp v196, v196, v196 quad_perm:[2,3,0,1] row_mask:0xf bank_mask:0xf bound_ctrl:1
	v_add_f32_dpp v198, v198, v198 quad_perm:[1,0,3,2] row_mask:0xf bank_mask:0xf bound_ctrl:1
	ds_write_b32 v100, v198 offset:2048
	v_add_f32_dpp v196, v196, v196 row_half_mirror row_mask:0xf bank_mask:0xf bound_ctrl:1
	s_nop 1
	v_add_f32_dpp v196, v196, v196 row_mirror row_mask:0xf bank_mask:0xf bound_ctrl:1
	v_mov_b32_e32 v197, v196
	s_nop 1
	v_permlane16_swap_b32_e32 v196, v197
	v_add_f32_e32 v196, v196, v197
	v_pk_fma_f32 v[82:83], v[196:197], v[180:181], v[194:195] op_sel_hi:[0,1,1] neg_lo:[1,0,0] neg_hi:[1,0,0]
	ds_read_b64 v[174:175], v98 offset:26368
	ds_read_b64 v[176:177], v98 offset:18176
	ds_read_b64 v[178:179], v98 offset:9984
	ds_read_b64 v[180:181], v98 offset:34560
	ds_read_b32 v182, v99 offset:448
	ds_read_b64 v[186:187], v98 offset:1536
	s_waitcnt lgkmcnt(7)
	v_pk_mul_f32 v[190:191], v[82:83], v[162:163]
	v_add_f32_e32 v196, v190, v191
	v_pk_mul_f32 v[192:193], v[82:83], v[188:189]
	v_pk_mul_f32 v[194:195], v[82:83], v[164:165]
	v_add_f32_dpp v196, v196, v196 quad_perm:[1,0,3,2] row_mask:0xf bank_mask:0xf bound_ctrl:1
	v_add_f32_e32 v198, v192, v193
	v_pk_fma_f32 v[194:195], v[170:171], v[166:167], v[194:195] op_sel_hi:[0,1,1]
	v_add_f32_dpp v196, v196, v196 quad_perm:[2,3,0,1] row_mask:0xf bank_mask:0xf bound_ctrl:1
	v_add_f32_dpp v198, v198, v198 quad_perm:[1,0,3,2] row_mask:0xf bank_mask:0xf bound_ctrl:1
	ds_write_b32 v100, v198 offset:2560
	v_add_f32_dpp v196, v196, v196 row_half_mirror row_mask:0xf bank_mask:0xf bound_ctrl:1
	s_nop 1
	v_add_f32_dpp v196, v196, v196 row_mirror row_mask:0xf bank_mask:0xf bound_ctrl:1
	v_mov_b32_e32 v197, v196
	s_nop 1
	v_permlane16_swap_b32_e32 v196, v197
	v_add_f32_e32 v196, v196, v197
	v_pk_fma_f32 v[82:83], v[196:197], v[168:169], v[194:195] op_sel_hi:[0,1,1] neg_lo:[1,0,0] neg_hi:[1,0,0]
	ds_read_b64 v[162:163], v98 offset:26624
	ds_read_b64 v[164:165], v98 offset:18432
	ds_read_b64 v[166:167], v98 offset:10240
	ds_read_b64 v[168:169], v98 offset:34816
	ds_read_b32 v170, v99 offset:512
	ds_read_b64 v[188:189], v98 offset:1792
	s_waitcnt lgkmcnt(7)
	v_pk_mul_f32 v[190:191], v[82:83], v[174:175]
	v_add_f32_e32 v196, v190, v191
	v_pk_mul_f32 v[192:193], v[82:83], v[186:187]
	v_pk_mul_f32 v[194:195], v[82:83], v[176:177]
	v_add_f32_dpp v196, v196, v196 quad_perm:[1,0,3,2] row_mask:0xf bank_mask:0xf bound_ctrl:1
	v_add_f32_e32 v198, v192, v193
	v_pk_fma_f32 v[194:195], v[182:183], v[178:179], v[194:195] op_sel_hi:[0,1,1]
	v_add_f32_dpp v196, v196, v196 quad_perm:[2,3,0,1] row_mask:0xf bank_mask:0xf bound_ctrl:1
	v_add_f32_dpp v198, v198, v198 quad_perm:[1,0,3,2] row_mask:0xf bank_mask:0xf bound_ctrl:1
	ds_write_b32 v100, v198 offset:3072
	v_add_f32_dpp v196, v196, v196 row_half_mirror row_mask:0xf bank_mask:0xf bound_ctrl:1
	s_nop 1
	v_add_f32_dpp v196, v196, v196 row_mirror row_mask:0xf bank_mask:0xf bound_ctrl:1
	v_mov_b32_e32 v197, v196
	s_nop 1
	v_permlane16_swap_b32_e32 v196, v197
	v_add_f32_e32 v196, v196, v197
	v_pk_fma_f32 v[82:83], v[196:197], v[180:181], v[194:195] op_sel_hi:[0,1,1] neg_lo:[1,0,0] neg_hi:[1,0,0]
	ds_read_b64 v[174:175], v98 offset:26880
	ds_read_b64 v[176:177], v98 offset:18688
	ds_read_b64 v[178:179], v98 offset:10496
	ds_read_b64 v[180:181], v98 offset:35072
	ds_read_b32 v182, v99 offset:576
	ds_read_b64 v[186:187], v98 offset:2048
	s_waitcnt lgkmcnt(7)
	v_pk_mul_f32 v[190:191], v[82:83], v[162:163]
	v_add_f32_e32 v196, v190, v191
	v_pk_mul_f32 v[192:193], v[82:83], v[188:189]
	v_pk_mul_f32 v[194:195], v[82:83], v[164:165]
	v_add_f32_dpp v196, v196, v196 quad_perm:[1,0,3,2] row_mask:0xf bank_mask:0xf bound_ctrl:1
	v_add_f32_e32 v198, v192, v193
	v_pk_fma_f32 v[194:195], v[170:171], v[166:167], v[194:195] op_sel_hi:[0,1,1]
	v_add_f32_dpp v196, v196, v196 quad_perm:[2,3,0,1] row_mask:0xf bank_mask:0xf bound_ctrl:1
	v_add_f32_dpp v198, v198, v198 quad_perm:[1,0,3,2] row_mask:0xf bank_mask:0xf bound_ctrl:1
	ds_write_b32 v100, v198 offset:3584
	v_add_f32_dpp v196, v196, v196 row_half_mirror row_mask:0xf bank_mask:0xf bound_ctrl:1
	s_nop 1
	v_add_f32_dpp v196, v196, v196 row_mirror row_mask:0xf bank_mask:0xf bound_ctrl:1
	v_mov_b32_e32 v197, v196
	s_nop 1
	v_permlane16_swap_b32_e32 v196, v197
	v_add_f32_e32 v196, v196, v197
	v_pk_fma_f32 v[82:83], v[196:197], v[168:169], v[194:195] op_sel_hi:[0,1,1] neg_lo:[1,0,0] neg_hi:[1,0,0]
	ds_read_b64 v[162:163], v98 offset:27136
	ds_read_b64 v[164:165], v98 offset:18944
	ds_read_b64 v[166:167], v98 offset:10752
	ds_read_b64 v[168:169], v98 offset:35328
	ds_read_b32 v170, v99 offset:640
	ds_read_b64 v[188:189], v98 offset:2304
	s_waitcnt lgkmcnt(7)
	v_pk_mul_f32 v[190:191], v[82:83], v[174:175]
	v_add_f32_e32 v196, v190, v191
	v_pk_mul_f32 v[192:193], v[82:83], v[186:187]
	v_pk_mul_f32 v[194:195], v[82:83], v[176:177]
	v_add_f32_dpp v196, v196, v196 quad_perm:[1,0,3,2] row_mask:0xf bank_mask:0xf bound_ctrl:1
	v_add_f32_e32 v198, v192, v193
	v_pk_fma_f32 v[194:195], v[182:183], v[178:179], v[194:195] op_sel_hi:[0,1,1]
	v_add_f32_dpp v196, v196, v196 quad_perm:[2,3,0,1] row_mask:0xf bank_mask:0xf bound_ctrl:1
	v_add_f32_dpp v198, v198, v198 quad_perm:[1,0,3,2] row_mask:0xf bank_mask:0xf bound_ctrl:1
	ds_write_b32 v100, v198 offset:4096
	v_add_f32_dpp v196, v196, v196 row_half_mirror row_mask:0xf bank_mask:0xf bound_ctrl:1
	s_nop 1
	v_add_f32_dpp v196, v196, v196 row_mirror row_mask:0xf bank_mask:0xf bound_ctrl:1
	v_mov_b32_e32 v197, v196
	s_nop 1
	v_permlane16_swap_b32_e32 v196, v197
	v_add_f32_e32 v196, v196, v197
	v_pk_fma_f32 v[82:83], v[196:197], v[180:181], v[194:195] op_sel_hi:[0,1,1] neg_lo:[1,0,0] neg_hi:[1,0,0]
	ds_read_b64 v[174:175], v98 offset:27392
	ds_read_b64 v[176:177], v98 offset:19200
	ds_read_b64 v[178:179], v98 offset:11008
	ds_read_b64 v[180:181], v98 offset:35584
	ds_read_b32 v182, v99 offset:704
	ds_read_b64 v[186:187], v98 offset:2560
	s_waitcnt lgkmcnt(7)
	v_pk_mul_f32 v[190:191], v[82:83], v[162:163]
	v_add_f32_e32 v196, v190, v191
	v_pk_mul_f32 v[192:193], v[82:83], v[188:189]
	v_pk_mul_f32 v[194:195], v[82:83], v[164:165]
	v_add_f32_dpp v196, v196, v196 quad_perm:[1,0,3,2] row_mask:0xf bank_mask:0xf bound_ctrl:1
	v_add_f32_e32 v198, v192, v193
	v_pk_fma_f32 v[194:195], v[170:171], v[166:167], v[194:195] op_sel_hi:[0,1,1]
	v_add_f32_dpp v196, v196, v196 quad_perm:[2,3,0,1] row_mask:0xf bank_mask:0xf bound_ctrl:1
	v_add_f32_dpp v198, v198, v198 quad_perm:[1,0,3,2] row_mask:0xf bank_mask:0xf bound_ctrl:1
	ds_write_b32 v100, v198 offset:4608
	v_add_f32_dpp v196, v196, v196 row_half_mirror row_mask:0xf bank_mask:0xf bound_ctrl:1
	s_nop 1
	v_add_f32_dpp v196, v196, v196 row_mirror row_mask:0xf bank_mask:0xf bound_ctrl:1
	v_mov_b32_e32 v197, v196
	s_nop 1
	v_permlane16_swap_b32_e32 v196, v197
	v_add_f32_e32 v196, v196, v197
	v_pk_fma_f32 v[82:83], v[196:197], v[168:169], v[194:195] op_sel_hi:[0,1,1] neg_lo:[1,0,0] neg_hi:[1,0,0]
	ds_read_b64 v[162:163], v98 offset:27648
	ds_read_b64 v[164:165], v98 offset:19456
	ds_read_b64 v[166:167], v98 offset:11264
	ds_read_b64 v[168:169], v98 offset:35840
	ds_read_b32 v170, v99 offset:768
	ds_read_b64 v[188:189], v98 offset:2816
	s_waitcnt lgkmcnt(7)
	v_pk_mul_f32 v[190:191], v[82:83], v[174:175]
	v_add_f32_e32 v196, v190, v191
	v_pk_mul_f32 v[192:193], v[82:83], v[186:187]
	v_pk_mul_f32 v[194:195], v[82:83], v[176:177]
	v_add_f32_dpp v196, v196, v196 quad_perm:[1,0,3,2] row_mask:0xf bank_mask:0xf bound_ctrl:1
	v_add_f32_e32 v198, v192, v193
	v_pk_fma_f32 v[194:195], v[182:183], v[178:179], v[194:195] op_sel_hi:[0,1,1]
	v_add_f32_dpp v196, v196, v196 quad_perm:[2,3,0,1] row_mask:0xf bank_mask:0xf bound_ctrl:1
	v_add_f32_dpp v198, v198, v198 quad_perm:[1,0,3,2] row_mask:0xf bank_mask:0xf bound_ctrl:1
	ds_write_b32 v100, v198 offset:5120
	v_add_f32_dpp v196, v196, v196 row_half_mirror row_mask:0xf bank_mask:0xf bound_ctrl:1
	s_nop 1
	v_add_f32_dpp v196, v196, v196 row_mirror row_mask:0xf bank_mask:0xf bound_ctrl:1
	v_mov_b32_e32 v197, v196
	s_nop 1
	v_permlane16_swap_b32_e32 v196, v197
	v_add_f32_e32 v196, v196, v197
	v_pk_fma_f32 v[82:83], v[196:197], v[180:181], v[194:195] op_sel_hi:[0,1,1] neg_lo:[1,0,0] neg_hi:[1,0,0]
	ds_read_b64 v[174:175], v98 offset:27904
	ds_read_b64 v[176:177], v98 offset:19712
	ds_read_b64 v[178:179], v98 offset:11520
	ds_read_b64 v[180:181], v98 offset:36096
	ds_read_b32 v182, v99 offset:832
	ds_read_b64 v[186:187], v98 offset:3072
	s_waitcnt lgkmcnt(7)
	v_pk_mul_f32 v[190:191], v[82:83], v[162:163]
	v_add_f32_e32 v196, v190, v191
	v_pk_mul_f32 v[192:193], v[82:83], v[188:189]
	v_pk_mul_f32 v[194:195], v[82:83], v[164:165]
	v_add_f32_dpp v196, v196, v196 quad_perm:[1,0,3,2] row_mask:0xf bank_mask:0xf bound_ctrl:1
	v_add_f32_e32 v198, v192, v193
	v_pk_fma_f32 v[194:195], v[170:171], v[166:167], v[194:195] op_sel_hi:[0,1,1]
	v_add_f32_dpp v196, v196, v196 quad_perm:[2,3,0,1] row_mask:0xf bank_mask:0xf bound_ctrl:1
	v_add_f32_dpp v198, v198, v198 quad_perm:[1,0,3,2] row_mask:0xf bank_mask:0xf bound_ctrl:1
	ds_write_b32 v100, v198 offset:5632
	v_add_f32_dpp v196, v196, v196 row_half_mirror row_mask:0xf bank_mask:0xf bound_ctrl:1
	s_nop 1
	v_add_f32_dpp v196, v196, v196 row_mirror row_mask:0xf bank_mask:0xf bound_ctrl:1
	v_mov_b32_e32 v197, v196
	s_nop 1
	v_permlane16_swap_b32_e32 v196, v197
	v_add_f32_e32 v196, v196, v197
	v_pk_fma_f32 v[82:83], v[196:197], v[168:169], v[194:195] op_sel_hi:[0,1,1] neg_lo:[1,0,0] neg_hi:[1,0,0]
	ds_read_b64 v[162:163], v98 offset:28160
	ds_read_b64 v[164:165], v98 offset:19968
	ds_read_b64 v[166:167], v98 offset:11776
	ds_read_b64 v[168:169], v98 offset:36352
	ds_read_b32 v170, v99 offset:896
	ds_read_b64 v[188:189], v98 offset:3328
	s_waitcnt lgkmcnt(7)
	v_pk_mul_f32 v[190:191], v[82:83], v[174:175]
	v_add_f32_e32 v196, v190, v191
	v_pk_mul_f32 v[192:193], v[82:83], v[186:187]
	v_pk_mul_f32 v[194:195], v[82:83], v[176:177]
	v_add_f32_dpp v196, v196, v196 quad_perm:[1,0,3,2] row_mask:0xf bank_mask:0xf bound_ctrl:1
	v_add_f32_e32 v198, v192, v193
	v_pk_fma_f32 v[194:195], v[182:183], v[178:179], v[194:195] op_sel_hi:[0,1,1]
	v_add_f32_dpp v196, v196, v196 quad_perm:[2,3,0,1] row_mask:0xf bank_mask:0xf bound_ctrl:1
	v_add_f32_dpp v198, v198, v198 quad_perm:[1,0,3,2] row_mask:0xf bank_mask:0xf bound_ctrl:1
	ds_write_b32 v100, v198 offset:6144
	v_add_f32_dpp v196, v196, v196 row_half_mirror row_mask:0xf bank_mask:0xf bound_ctrl:1
	s_nop 1
	v_add_f32_dpp v196, v196, v196 row_mirror row_mask:0xf bank_mask:0xf bound_ctrl:1
	v_mov_b32_e32 v197, v196
	s_nop 1
	v_permlane16_swap_b32_e32 v196, v197
	v_add_f32_e32 v196, v196, v197
	v_pk_fma_f32 v[82:83], v[196:197], v[180:181], v[194:195] op_sel_hi:[0,1,1] neg_lo:[1,0,0] neg_hi:[1,0,0]
	ds_read_b64 v[174:175], v98 offset:28416
	ds_read_b64 v[176:177], v98 offset:20224
	ds_read_b64 v[178:179], v98 offset:12032
	ds_read_b64 v[180:181], v98 offset:36608
	ds_read_b32 v182, v99 offset:960
	ds_read_b64 v[186:187], v98 offset:3584
	s_waitcnt lgkmcnt(7)
	v_pk_mul_f32 v[190:191], v[82:83], v[162:163]
	v_add_f32_e32 v196, v190, v191
	v_pk_mul_f32 v[192:193], v[82:83], v[188:189]
	v_pk_mul_f32 v[194:195], v[82:83], v[164:165]
	v_add_f32_dpp v196, v196, v196 quad_perm:[1,0,3,2] row_mask:0xf bank_mask:0xf bound_ctrl:1
	v_add_f32_e32 v198, v192, v193
	v_pk_fma_f32 v[194:195], v[170:171], v[166:167], v[194:195] op_sel_hi:[0,1,1]
	v_add_f32_dpp v196, v196, v196 quad_perm:[2,3,0,1] row_mask:0xf bank_mask:0xf bound_ctrl:1
	v_add_f32_dpp v198, v198, v198 quad_perm:[1,0,3,2] row_mask:0xf bank_mask:0xf bound_ctrl:1
	ds_write_b32 v100, v198 offset:6656
	v_add_f32_dpp v196, v196, v196 row_half_mirror row_mask:0xf bank_mask:0xf bound_ctrl:1
	s_nop 1
	v_add_f32_dpp v196, v196, v196 row_mirror row_mask:0xf bank_mask:0xf bound_ctrl:1
	v_mov_b32_e32 v197, v196
	s_nop 1
	v_permlane16_swap_b32_e32 v196, v197
	v_add_f32_e32 v196, v196, v197
	v_pk_fma_f32 v[82:83], v[196:197], v[168:169], v[194:195] op_sel_hi:[0,1,1] neg_lo:[1,0,0] neg_hi:[1,0,0]
	ds_read_b64 v[162:163], v98 offset:28672
	ds_read_b64 v[164:165], v98 offset:20480
	ds_read_b64 v[166:167], v98 offset:12288
	ds_read_b64 v[168:169], v98 offset:36864
	ds_read_b32 v170, v99 offset:1024
	ds_read_b64 v[188:189], v98 offset:3840
	s_waitcnt lgkmcnt(7)
	v_pk_mul_f32 v[190:191], v[82:83], v[174:175]
	v_add_f32_e32 v196, v190, v191
	v_pk_mul_f32 v[192:193], v[82:83], v[186:187]
	v_pk_mul_f32 v[194:195], v[82:83], v[176:177]
	v_add_f32_dpp v196, v196, v196 quad_perm:[1,0,3,2] row_mask:0xf bank_mask:0xf bound_ctrl:1
	v_add_f32_e32 v198, v192, v193
	v_pk_fma_f32 v[194:195], v[182:183], v[178:179], v[194:195] op_sel_hi:[0,1,1]
	v_add_f32_dpp v196, v196, v196 quad_perm:[2,3,0,1] row_mask:0xf bank_mask:0xf bound_ctrl:1
	v_add_f32_dpp v198, v198, v198 quad_perm:[1,0,3,2] row_mask:0xf bank_mask:0xf bound_ctrl:1
	ds_write_b32 v100, v198 offset:7168
	v_add_f32_dpp v196, v196, v196 row_half_mirror row_mask:0xf bank_mask:0xf bound_ctrl:1
	s_nop 1
	v_add_f32_dpp v196, v196, v196 row_mirror row_mask:0xf bank_mask:0xf bound_ctrl:1
	v_mov_b32_e32 v197, v196
	s_nop 1
	v_permlane16_swap_b32_e32 v196, v197
	v_add_f32_e32 v196, v196, v197
	v_pk_fma_f32 v[82:83], v[196:197], v[180:181], v[194:195] op_sel_hi:[0,1,1] neg_lo:[1,0,0] neg_hi:[1,0,0]
	ds_read_b64 v[174:175], v98 offset:28928
	ds_read_b64 v[176:177], v98 offset:20736
	ds_read_b64 v[178:179], v98 offset:12544
	ds_read_b64 v[180:181], v98 offset:37120
	ds_read_b32 v182, v99 offset:1088
	ds_read_b64 v[186:187], v98 offset:4096
	s_waitcnt lgkmcnt(7)
	v_pk_mul_f32 v[190:191], v[82:83], v[162:163]
	v_add_f32_e32 v196, v190, v191
	v_pk_mul_f32 v[192:193], v[82:83], v[188:189]
	v_pk_mul_f32 v[194:195], v[82:83], v[164:165]
	v_add_f32_dpp v196, v196, v196 quad_perm:[1,0,3,2] row_mask:0xf bank_mask:0xf bound_ctrl:1
	v_add_f32_e32 v198, v192, v193
	v_pk_fma_f32 v[194:195], v[170:171], v[166:167], v[194:195] op_sel_hi:[0,1,1]
	v_add_f32_dpp v196, v196, v196 quad_perm:[2,3,0,1] row_mask:0xf bank_mask:0xf bound_ctrl:1
	v_add_f32_dpp v198, v198, v198 quad_perm:[1,0,3,2] row_mask:0xf bank_mask:0xf bound_ctrl:1
	ds_write_b32 v100, v198 offset:7680
	v_add_f32_dpp v196, v196, v196 row_half_mirror row_mask:0xf bank_mask:0xf bound_ctrl:1
	s_nop 1
	v_add_f32_dpp v196, v196, v196 row_mirror row_mask:0xf bank_mask:0xf bound_ctrl:1
	v_mov_b32_e32 v197, v196
	s_nop 1
	v_permlane16_swap_b32_e32 v196, v197
	v_add_f32_e32 v196, v196, v197
	v_pk_fma_f32 v[82:83], v[196:197], v[168:169], v[194:195] op_sel_hi:[0,1,1] neg_lo:[1,0,0] neg_hi:[1,0,0]
	ds_read_b64 v[162:163], v98 offset:29184
	ds_read_b64 v[164:165], v98 offset:20992
	ds_read_b64 v[166:167], v98 offset:12800
	ds_read_b64 v[168:169], v98 offset:37376
	ds_read_b32 v170, v99 offset:1152
	ds_read_b64 v[188:189], v98 offset:4352
	s_waitcnt lgkmcnt(7)
	v_pk_mul_f32 v[190:191], v[82:83], v[174:175]
	v_add_f32_e32 v196, v190, v191
	v_pk_mul_f32 v[192:193], v[82:83], v[186:187]
	v_pk_mul_f32 v[194:195], v[82:83], v[176:177]
	v_add_f32_dpp v196, v196, v196 quad_perm:[1,0,3,2] row_mask:0xf bank_mask:0xf bound_ctrl:1
	v_add_f32_e32 v198, v192, v193
	v_pk_fma_f32 v[194:195], v[182:183], v[178:179], v[194:195] op_sel_hi:[0,1,1]
	v_add_f32_dpp v196, v196, v196 quad_perm:[2,3,0,1] row_mask:0xf bank_mask:0xf bound_ctrl:1
	v_add_f32_dpp v198, v198, v198 quad_perm:[1,0,3,2] row_mask:0xf bank_mask:0xf bound_ctrl:1
	ds_write_b32 v100, v198 offset:8192
	v_add_f32_dpp v196, v196, v196 row_half_mirror row_mask:0xf bank_mask:0xf bound_ctrl:1
	s_nop 1
	v_add_f32_dpp v196, v196, v196 row_mirror row_mask:0xf bank_mask:0xf bound_ctrl:1
	v_mov_b32_e32 v197, v196
	s_nop 1
	v_permlane16_swap_b32_e32 v196, v197
	v_add_f32_e32 v196, v196, v197
	v_pk_fma_f32 v[82:83], v[196:197], v[180:181], v[194:195] op_sel_hi:[0,1,1] neg_lo:[1,0,0] neg_hi:[1,0,0]
	ds_read_b64 v[174:175], v98 offset:29440
	ds_read_b64 v[176:177], v98 offset:21248
	ds_read_b64 v[178:179], v98 offset:13056
	ds_read_b64 v[180:181], v98 offset:37632
	ds_read_b32 v182, v99 offset:1216
	ds_read_b64 v[186:187], v98 offset:4608
	s_waitcnt lgkmcnt(7)
	v_pk_mul_f32 v[190:191], v[82:83], v[162:163]
	v_add_f32_e32 v196, v190, v191
	v_pk_mul_f32 v[192:193], v[82:83], v[188:189]
	v_pk_mul_f32 v[194:195], v[82:83], v[164:165]
	v_add_f32_dpp v196, v196, v196 quad_perm:[1,0,3,2] row_mask:0xf bank_mask:0xf bound_ctrl:1
	v_add_f32_e32 v198, v192, v193
	v_pk_fma_f32 v[194:195], v[170:171], v[166:167], v[194:195] op_sel_hi:[0,1,1]
	v_add_f32_dpp v196, v196, v196 quad_perm:[2,3,0,1] row_mask:0xf bank_mask:0xf bound_ctrl:1
	v_add_f32_dpp v198, v198, v198 quad_perm:[1,0,3,2] row_mask:0xf bank_mask:0xf bound_ctrl:1
	ds_write_b32 v100, v198 offset:8704
	v_add_f32_dpp v196, v196, v196 row_half_mirror row_mask:0xf bank_mask:0xf bound_ctrl:1
	s_nop 1
	v_add_f32_dpp v196, v196, v196 row_mirror row_mask:0xf bank_mask:0xf bound_ctrl:1
	v_mov_b32_e32 v197, v196
	s_nop 1
	v_permlane16_swap_b32_e32 v196, v197
	v_add_f32_e32 v196, v196, v197
	v_pk_fma_f32 v[82:83], v[196:197], v[168:169], v[194:195] op_sel_hi:[0,1,1] neg_lo:[1,0,0] neg_hi:[1,0,0]
	ds_read_b64 v[162:163], v98 offset:29696
	ds_read_b64 v[164:165], v98 offset:21504
	ds_read_b64 v[166:167], v98 offset:13312
	ds_read_b64 v[168:169], v98 offset:37888
	ds_read_b32 v170, v99 offset:1280
	ds_read_b64 v[188:189], v98 offset:4864
	s_waitcnt lgkmcnt(7)
	v_pk_mul_f32 v[190:191], v[82:83], v[174:175]
	v_add_f32_e32 v196, v190, v191
	v_pk_mul_f32 v[192:193], v[82:83], v[186:187]
	v_pk_mul_f32 v[194:195], v[82:83], v[176:177]
	v_add_f32_dpp v196, v196, v196 quad_perm:[1,0,3,2] row_mask:0xf bank_mask:0xf bound_ctrl:1
	v_add_f32_e32 v198, v192, v193
	v_pk_fma_f32 v[194:195], v[182:183], v[178:179], v[194:195] op_sel_hi:[0,1,1]
	v_add_f32_dpp v196, v196, v196 quad_perm:[2,3,0,1] row_mask:0xf bank_mask:0xf bound_ctrl:1
	v_add_f32_dpp v198, v198, v198 quad_perm:[1,0,3,2] row_mask:0xf bank_mask:0xf bound_ctrl:1
	ds_write_b32 v100, v198 offset:9216
	v_add_f32_dpp v196, v196, v196 row_half_mirror row_mask:0xf bank_mask:0xf bound_ctrl:1
	s_nop 1
	v_add_f32_dpp v196, v196, v196 row_mirror row_mask:0xf bank_mask:0xf bound_ctrl:1
	v_mov_b32_e32 v197, v196
	s_nop 1
	v_permlane16_swap_b32_e32 v196, v197
	v_add_f32_e32 v196, v196, v197
	v_pk_fma_f32 v[82:83], v[196:197], v[180:181], v[194:195] op_sel_hi:[0,1,1] neg_lo:[1,0,0] neg_hi:[1,0,0]
	ds_read_b64 v[174:175], v98 offset:29952
	ds_read_b64 v[176:177], v98 offset:21760
	ds_read_b64 v[178:179], v98 offset:13568
	ds_read_b64 v[180:181], v98 offset:38144
	ds_read_b32 v182, v99 offset:1344
	ds_read_b64 v[186:187], v98 offset:5120
	s_waitcnt lgkmcnt(7)
	v_pk_mul_f32 v[190:191], v[82:83], v[162:163]
	v_add_f32_e32 v196, v190, v191
	v_pk_mul_f32 v[192:193], v[82:83], v[188:189]
	v_pk_mul_f32 v[194:195], v[82:83], v[164:165]
	v_add_f32_dpp v196, v196, v196 quad_perm:[1,0,3,2] row_mask:0xf bank_mask:0xf bound_ctrl:1
	v_add_f32_e32 v198, v192, v193
	v_pk_fma_f32 v[194:195], v[170:171], v[166:167], v[194:195] op_sel_hi:[0,1,1]
	v_add_f32_dpp v196, v196, v196 quad_perm:[2,3,0,1] row_mask:0xf bank_mask:0xf bound_ctrl:1
	v_add_f32_dpp v198, v198, v198 quad_perm:[1,0,3,2] row_mask:0xf bank_mask:0xf bound_ctrl:1
	ds_write_b32 v100, v198 offset:9728
	v_add_f32_dpp v196, v196, v196 row_half_mirror row_mask:0xf bank_mask:0xf bound_ctrl:1
	s_nop 1
	v_add_f32_dpp v196, v196, v196 row_mirror row_mask:0xf bank_mask:0xf bound_ctrl:1
	v_mov_b32_e32 v197, v196
	s_nop 1
	v_permlane16_swap_b32_e32 v196, v197
	v_add_f32_e32 v196, v196, v197
	v_pk_fma_f32 v[82:83], v[196:197], v[168:169], v[194:195] op_sel_hi:[0,1,1] neg_lo:[1,0,0] neg_hi:[1,0,0]
	ds_read_b64 v[162:163], v98 offset:30208
	ds_read_b64 v[164:165], v98 offset:22016
	ds_read_b64 v[166:167], v98 offset:13824
	ds_read_b64 v[168:169], v98 offset:38400
	ds_read_b32 v170, v99 offset:1408
	ds_read_b64 v[188:189], v98 offset:5376
	s_waitcnt lgkmcnt(7)
	v_pk_mul_f32 v[190:191], v[82:83], v[174:175]
	v_add_f32_e32 v196, v190, v191
	v_pk_mul_f32 v[192:193], v[82:83], v[186:187]
	v_pk_mul_f32 v[194:195], v[82:83], v[176:177]
	v_add_f32_dpp v196, v196, v196 quad_perm:[1,0,3,2] row_mask:0xf bank_mask:0xf bound_ctrl:1
	v_add_f32_e32 v198, v192, v193
	v_pk_fma_f32 v[194:195], v[182:183], v[178:179], v[194:195] op_sel_hi:[0,1,1]
	v_add_f32_dpp v196, v196, v196 quad_perm:[2,3,0,1] row_mask:0xf bank_mask:0xf bound_ctrl:1
	v_add_f32_dpp v198, v198, v198 quad_perm:[1,0,3,2] row_mask:0xf bank_mask:0xf bound_ctrl:1
	ds_write_b32 v100, v198 offset:10240
	v_add_f32_dpp v196, v196, v196 row_half_mirror row_mask:0xf bank_mask:0xf bound_ctrl:1
	s_nop 1
	v_add_f32_dpp v196, v196, v196 row_mirror row_mask:0xf bank_mask:0xf bound_ctrl:1
	v_mov_b32_e32 v197, v196
	s_nop 1
	v_permlane16_swap_b32_e32 v196, v197
	v_add_f32_e32 v196, v196, v197
	v_pk_fma_f32 v[82:83], v[196:197], v[180:181], v[194:195] op_sel_hi:[0,1,1] neg_lo:[1,0,0] neg_hi:[1,0,0]
	ds_read_b64 v[174:175], v98 offset:30464
	ds_read_b64 v[176:177], v98 offset:22272
	ds_read_b64 v[178:179], v98 offset:14080
	ds_read_b64 v[180:181], v98 offset:38656
	ds_read_b32 v182, v99 offset:1472
	ds_read_b64 v[186:187], v98 offset:5632
	s_waitcnt lgkmcnt(7)
	v_pk_mul_f32 v[190:191], v[82:83], v[162:163]
	v_add_f32_e32 v196, v190, v191
	v_pk_mul_f32 v[192:193], v[82:83], v[188:189]
	v_pk_mul_f32 v[194:195], v[82:83], v[164:165]
	v_add_f32_dpp v196, v196, v196 quad_perm:[1,0,3,2] row_mask:0xf bank_mask:0xf bound_ctrl:1
	v_add_f32_e32 v198, v192, v193
	v_pk_fma_f32 v[194:195], v[170:171], v[166:167], v[194:195] op_sel_hi:[0,1,1]
	v_add_f32_dpp v196, v196, v196 quad_perm:[2,3,0,1] row_mask:0xf bank_mask:0xf bound_ctrl:1
	v_add_f32_dpp v198, v198, v198 quad_perm:[1,0,3,2] row_mask:0xf bank_mask:0xf bound_ctrl:1
	ds_write_b32 v100, v198 offset:10752
	v_add_f32_dpp v196, v196, v196 row_half_mirror row_mask:0xf bank_mask:0xf bound_ctrl:1
	s_nop 1
	v_add_f32_dpp v196, v196, v196 row_mirror row_mask:0xf bank_mask:0xf bound_ctrl:1
	v_mov_b32_e32 v197, v196
	s_nop 1
	v_permlane16_swap_b32_e32 v196, v197
	v_add_f32_e32 v196, v196, v197
	v_pk_fma_f32 v[82:83], v[196:197], v[168:169], v[194:195] op_sel_hi:[0,1,1] neg_lo:[1,0,0] neg_hi:[1,0,0]
	ds_read_b64 v[162:163], v98 offset:30720
	ds_read_b64 v[164:165], v98 offset:22528
	ds_read_b64 v[166:167], v98 offset:14336
	ds_read_b64 v[168:169], v98 offset:38912
	ds_read_b32 v170, v99 offset:1536
	ds_read_b64 v[188:189], v98 offset:5888
	s_waitcnt lgkmcnt(7)
	v_pk_mul_f32 v[190:191], v[82:83], v[174:175]
	v_add_f32_e32 v196, v190, v191
	v_pk_mul_f32 v[192:193], v[82:83], v[186:187]
	v_pk_mul_f32 v[194:195], v[82:83], v[176:177]
	v_add_f32_dpp v196, v196, v196 quad_perm:[1,0,3,2] row_mask:0xf bank_mask:0xf bound_ctrl:1
	v_add_f32_e32 v198, v192, v193
	v_pk_fma_f32 v[194:195], v[182:183], v[178:179], v[194:195] op_sel_hi:[0,1,1]
	v_add_f32_dpp v196, v196, v196 quad_perm:[2,3,0,1] row_mask:0xf bank_mask:0xf bound_ctrl:1
	v_add_f32_dpp v198, v198, v198 quad_perm:[1,0,3,2] row_mask:0xf bank_mask:0xf bound_ctrl:1
	ds_write_b32 v100, v198 offset:11264
	v_add_f32_dpp v196, v196, v196 row_half_mirror row_mask:0xf bank_mask:0xf bound_ctrl:1
	s_nop 1
	v_add_f32_dpp v196, v196, v196 row_mirror row_mask:0xf bank_mask:0xf bound_ctrl:1
	v_mov_b32_e32 v197, v196
	s_nop 1
	v_permlane16_swap_b32_e32 v196, v197
	v_add_f32_e32 v196, v196, v197
	v_pk_fma_f32 v[82:83], v[196:197], v[180:181], v[194:195] op_sel_hi:[0,1,1] neg_lo:[1,0,0] neg_hi:[1,0,0]
	ds_read_b64 v[174:175], v98 offset:30976
	ds_read_b64 v[176:177], v98 offset:22784
	ds_read_b64 v[178:179], v98 offset:14592
	ds_read_b64 v[180:181], v98 offset:39168
	ds_read_b32 v182, v99 offset:1600
	ds_read_b64 v[186:187], v98 offset:6144
	s_waitcnt lgkmcnt(7)
	v_pk_mul_f32 v[190:191], v[82:83], v[162:163]
	v_add_f32_e32 v196, v190, v191
	v_pk_mul_f32 v[192:193], v[82:83], v[188:189]
	v_pk_mul_f32 v[194:195], v[82:83], v[164:165]
	v_add_f32_dpp v196, v196, v196 quad_perm:[1,0,3,2] row_mask:0xf bank_mask:0xf bound_ctrl:1
	v_add_f32_e32 v198, v192, v193
	v_pk_fma_f32 v[194:195], v[170:171], v[166:167], v[194:195] op_sel_hi:[0,1,1]
	v_add_f32_dpp v196, v196, v196 quad_perm:[2,3,0,1] row_mask:0xf bank_mask:0xf bound_ctrl:1
	v_add_f32_dpp v198, v198, v198 quad_perm:[1,0,3,2] row_mask:0xf bank_mask:0xf bound_ctrl:1
	ds_write_b32 v100, v198 offset:11776
	v_add_f32_dpp v196, v196, v196 row_half_mirror row_mask:0xf bank_mask:0xf bound_ctrl:1
	s_nop 1
	v_add_f32_dpp v196, v196, v196 row_mirror row_mask:0xf bank_mask:0xf bound_ctrl:1
	v_mov_b32_e32 v197, v196
	s_nop 1
	v_permlane16_swap_b32_e32 v196, v197
	v_add_f32_e32 v196, v196, v197
	v_pk_fma_f32 v[82:83], v[196:197], v[168:169], v[194:195] op_sel_hi:[0,1,1] neg_lo:[1,0,0] neg_hi:[1,0,0]
	ds_read_b64 v[162:163], v98 offset:31232
	ds_read_b64 v[164:165], v98 offset:23040
	ds_read_b64 v[166:167], v98 offset:14848
	ds_read_b64 v[168:169], v98 offset:39424
	ds_read_b32 v170, v99 offset:1664
	ds_read_b64 v[188:189], v98 offset:6400
	s_waitcnt lgkmcnt(7)
	v_pk_mul_f32 v[190:191], v[82:83], v[174:175]
	v_add_f32_e32 v196, v190, v191
	v_pk_mul_f32 v[192:193], v[82:83], v[186:187]
	v_pk_mul_f32 v[194:195], v[82:83], v[176:177]
	v_add_f32_dpp v196, v196, v196 quad_perm:[1,0,3,2] row_mask:0xf bank_mask:0xf bound_ctrl:1
	v_add_f32_e32 v198, v192, v193
	v_pk_fma_f32 v[194:195], v[182:183], v[178:179], v[194:195] op_sel_hi:[0,1,1]
	v_add_f32_dpp v196, v196, v196 quad_perm:[2,3,0,1] row_mask:0xf bank_mask:0xf bound_ctrl:1
	v_add_f32_dpp v198, v198, v198 quad_perm:[1,0,3,2] row_mask:0xf bank_mask:0xf bound_ctrl:1
	ds_write_b32 v100, v198 offset:12288
	v_add_f32_dpp v196, v196, v196 row_half_mirror row_mask:0xf bank_mask:0xf bound_ctrl:1
	s_nop 1
	v_add_f32_dpp v196, v196, v196 row_mirror row_mask:0xf bank_mask:0xf bound_ctrl:1
	v_mov_b32_e32 v197, v196
	s_nop 1
	v_permlane16_swap_b32_e32 v196, v197
	v_add_f32_e32 v196, v196, v197
	v_pk_fma_f32 v[82:83], v[196:197], v[180:181], v[194:195] op_sel_hi:[0,1,1] neg_lo:[1,0,0] neg_hi:[1,0,0]
	ds_read_b64 v[174:175], v98 offset:31488
	ds_read_b64 v[176:177], v98 offset:23296
	ds_read_b64 v[178:179], v98 offset:15104
	ds_read_b64 v[180:181], v98 offset:39680
	ds_read_b32 v182, v99 offset:1728
	ds_read_b64 v[186:187], v98 offset:6656
	s_waitcnt lgkmcnt(7)
	v_pk_mul_f32 v[190:191], v[82:83], v[162:163]
	v_add_f32_e32 v196, v190, v191
	v_pk_mul_f32 v[192:193], v[82:83], v[188:189]
	v_pk_mul_f32 v[194:195], v[82:83], v[164:165]
	v_add_f32_dpp v196, v196, v196 quad_perm:[1,0,3,2] row_mask:0xf bank_mask:0xf bound_ctrl:1
	v_add_f32_e32 v198, v192, v193
	v_pk_fma_f32 v[194:195], v[170:171], v[166:167], v[194:195] op_sel_hi:[0,1,1]
	v_add_f32_dpp v196, v196, v196 quad_perm:[2,3,0,1] row_mask:0xf bank_mask:0xf bound_ctrl:1
	v_add_f32_dpp v198, v198, v198 quad_perm:[1,0,3,2] row_mask:0xf bank_mask:0xf bound_ctrl:1
	ds_write_b32 v100, v198 offset:12800
	v_add_f32_dpp v196, v196, v196 row_half_mirror row_mask:0xf bank_mask:0xf bound_ctrl:1
	s_nop 1
	v_add_f32_dpp v196, v196, v196 row_mirror row_mask:0xf bank_mask:0xf bound_ctrl:1
	v_mov_b32_e32 v197, v196
	s_nop 1
	v_permlane16_swap_b32_e32 v196, v197
	v_add_f32_e32 v196, v196, v197
	v_pk_fma_f32 v[82:83], v[196:197], v[168:169], v[194:195] op_sel_hi:[0,1,1] neg_lo:[1,0,0] neg_hi:[1,0,0]
	ds_read_b64 v[162:163], v98 offset:31744
	ds_read_b64 v[164:165], v98 offset:23552
	ds_read_b64 v[166:167], v98 offset:15360
	ds_read_b64 v[168:169], v98 offset:39936
	ds_read_b32 v170, v99 offset:1792
	ds_read_b64 v[188:189], v98 offset:6912
	s_waitcnt lgkmcnt(7)
	v_pk_mul_f32 v[190:191], v[82:83], v[174:175]
	v_add_f32_e32 v196, v190, v191
	v_pk_mul_f32 v[192:193], v[82:83], v[186:187]
	v_pk_mul_f32 v[194:195], v[82:83], v[176:177]
	v_add_f32_dpp v196, v196, v196 quad_perm:[1,0,3,2] row_mask:0xf bank_mask:0xf bound_ctrl:1
	v_add_f32_e32 v198, v192, v193
	v_pk_fma_f32 v[194:195], v[182:183], v[178:179], v[194:195] op_sel_hi:[0,1,1]
	v_add_f32_dpp v196, v196, v196 quad_perm:[2,3,0,1] row_mask:0xf bank_mask:0xf bound_ctrl:1
	v_add_f32_dpp v198, v198, v198 quad_perm:[1,0,3,2] row_mask:0xf bank_mask:0xf bound_ctrl:1
	ds_write_b32 v100, v198 offset:13312
	v_add_f32_dpp v196, v196, v196 row_half_mirror row_mask:0xf bank_mask:0xf bound_ctrl:1
	s_nop 1
	v_add_f32_dpp v196, v196, v196 row_mirror row_mask:0xf bank_mask:0xf bound_ctrl:1
	v_mov_b32_e32 v197, v196
	s_nop 1
	v_permlane16_swap_b32_e32 v196, v197
	v_add_f32_e32 v196, v196, v197
	v_pk_fma_f32 v[82:83], v[196:197], v[180:181], v[194:195] op_sel_hi:[0,1,1] neg_lo:[1,0,0] neg_hi:[1,0,0]
	ds_read_b64 v[174:175], v98 offset:32000
	ds_read_b64 v[176:177], v98 offset:23808
	ds_read_b64 v[178:179], v98 offset:15616
	ds_read_b64 v[180:181], v98 offset:40192
	ds_read_b32 v182, v99 offset:1856
	ds_read_b64 v[186:187], v98 offset:7168
	s_waitcnt lgkmcnt(7)
	v_pk_mul_f32 v[190:191], v[82:83], v[162:163]
	v_add_f32_e32 v196, v190, v191
	v_pk_mul_f32 v[192:193], v[82:83], v[188:189]
	v_pk_mul_f32 v[194:195], v[82:83], v[164:165]
	v_add_f32_dpp v196, v196, v196 quad_perm:[1,0,3,2] row_mask:0xf bank_mask:0xf bound_ctrl:1
	v_add_f32_e32 v198, v192, v193
	v_pk_fma_f32 v[194:195], v[170:171], v[166:167], v[194:195] op_sel_hi:[0,1,1]
	v_add_f32_dpp v196, v196, v196 quad_perm:[2,3,0,1] row_mask:0xf bank_mask:0xf bound_ctrl:1
	v_add_f32_dpp v198, v198, v198 quad_perm:[1,0,3,2] row_mask:0xf bank_mask:0xf bound_ctrl:1
	ds_write_b32 v100, v198 offset:13824
	v_add_f32_dpp v196, v196, v196 row_half_mirror row_mask:0xf bank_mask:0xf bound_ctrl:1
	s_nop 1
	v_add_f32_dpp v196, v196, v196 row_mirror row_mask:0xf bank_mask:0xf bound_ctrl:1
	v_mov_b32_e32 v197, v196
	s_nop 1
	v_permlane16_swap_b32_e32 v196, v197
	v_add_f32_e32 v196, v196, v197
	v_pk_fma_f32 v[82:83], v[196:197], v[168:169], v[194:195] op_sel_hi:[0,1,1] neg_lo:[1,0,0] neg_hi:[1,0,0]
	ds_read_b64 v[162:163], v98 offset:32256
	ds_read_b64 v[164:165], v98 offset:24064
	ds_read_b64 v[166:167], v98 offset:15872
	ds_read_b64 v[168:169], v98 offset:40448
	ds_read_b32 v170, v99 offset:1920
	ds_read_b64 v[188:189], v98 offset:7424
	s_waitcnt lgkmcnt(7)
	v_pk_mul_f32 v[190:191], v[82:83], v[174:175]
	v_add_f32_e32 v196, v190, v191
	v_pk_mul_f32 v[192:193], v[82:83], v[186:187]
	v_pk_mul_f32 v[194:195], v[82:83], v[176:177]
	v_add_f32_dpp v196, v196, v196 quad_perm:[1,0,3,2] row_mask:0xf bank_mask:0xf bound_ctrl:1
	v_add_f32_e32 v198, v192, v193
	v_pk_fma_f32 v[194:195], v[182:183], v[178:179], v[194:195] op_sel_hi:[0,1,1]
	v_add_f32_dpp v196, v196, v196 quad_perm:[2,3,0,1] row_mask:0xf bank_mask:0xf bound_ctrl:1
	v_add_f32_dpp v198, v198, v198 quad_perm:[1,0,3,2] row_mask:0xf bank_mask:0xf bound_ctrl:1
	ds_write_b32 v100, v198 offset:14336
	v_add_f32_dpp v196, v196, v196 row_half_mirror row_mask:0xf bank_mask:0xf bound_ctrl:1
	s_nop 1
	v_add_f32_dpp v196, v196, v196 row_mirror row_mask:0xf bank_mask:0xf bound_ctrl:1
	v_mov_b32_e32 v197, v196
	s_nop 1
	v_permlane16_swap_b32_e32 v196, v197
	v_add_f32_e32 v196, v196, v197
	v_pk_fma_f32 v[82:83], v[196:197], v[180:181], v[194:195] op_sel_hi:[0,1,1] neg_lo:[1,0,0] neg_hi:[1,0,0]
	ds_read_b64 v[174:175], v98 offset:32512
	ds_read_b64 v[176:177], v98 offset:24320
	ds_read_b64 v[178:179], v98 offset:16128
	ds_read_b64 v[180:181], v98 offset:40704
	ds_read_b32 v182, v99 offset:1984
	ds_read_b64 v[186:187], v98 offset:7680
	s_waitcnt lgkmcnt(7)
	v_pk_mul_f32 v[190:191], v[82:83], v[162:163]
	v_add_f32_e32 v196, v190, v191
	v_pk_mul_f32 v[192:193], v[82:83], v[188:189]
	v_pk_mul_f32 v[194:195], v[82:83], v[164:165]
	v_add_f32_dpp v196, v196, v196 quad_perm:[1,0,3,2] row_mask:0xf bank_mask:0xf bound_ctrl:1
	v_add_f32_e32 v198, v192, v193
	v_pk_fma_f32 v[194:195], v[170:171], v[166:167], v[194:195] op_sel_hi:[0,1,1]
	v_add_f32_dpp v196, v196, v196 quad_perm:[2,3,0,1] row_mask:0xf bank_mask:0xf bound_ctrl:1
	v_add_f32_dpp v198, v198, v198 quad_perm:[1,0,3,2] row_mask:0xf bank_mask:0xf bound_ctrl:1
	ds_write_b32 v100, v198 offset:14848
	v_add_f32_dpp v196, v196, v196 row_half_mirror row_mask:0xf bank_mask:0xf bound_ctrl:1
	s_nop 1
	v_add_f32_dpp v196, v196, v196 row_mirror row_mask:0xf bank_mask:0xf bound_ctrl:1
	v_mov_b32_e32 v197, v196
	s_nop 1
	v_permlane16_swap_b32_e32 v196, v197
	v_add_f32_e32 v196, v196, v197
	v_pk_fma_f32 v[82:83], v[196:197], v[168:169], v[194:195] op_sel_hi:[0,1,1] neg_lo:[1,0,0] neg_hi:[1,0,0]
	ds_read_b64 v[188:189], v98 offset:7936
	s_waitcnt lgkmcnt(2)
	v_pk_mul_f32 v[190:191], v[82:83], v[174:175]
	v_add_f32_e32 v196, v190, v191
	v_pk_mul_f32 v[192:193], v[82:83], v[186:187]
	v_pk_mul_f32 v[194:195], v[82:83], v[176:177]
	v_add_f32_dpp v196, v196, v196 quad_perm:[1,0,3,2] row_mask:0xf bank_mask:0xf bound_ctrl:1
	v_add_f32_e32 v198, v192, v193
	v_pk_fma_f32 v[194:195], v[182:183], v[178:179], v[194:195] op_sel_hi:[0,1,1]
	v_add_f32_dpp v196, v196, v196 quad_perm:[2,3,0,1] row_mask:0xf bank_mask:0xf bound_ctrl:1
	v_add_f32_dpp v198, v198, v198 quad_perm:[1,0,3,2] row_mask:0xf bank_mask:0xf bound_ctrl:1
	ds_write_b32 v100, v198 offset:15360
	v_add_f32_dpp v196, v196, v196 row_half_mirror row_mask:0xf bank_mask:0xf bound_ctrl:1
	s_nop 1
	v_add_f32_dpp v196, v196, v196 row_mirror row_mask:0xf bank_mask:0xf bound_ctrl:1
	v_mov_b32_e32 v197, v196
	s_nop 1
	v_permlane16_swap_b32_e32 v196, v197
	v_add_f32_e32 v196, v196, v197
	v_pk_fma_f32 v[82:83], v[196:197], v[180:181], v[194:195] op_sel_hi:[0,1,1] neg_lo:[1,0,0] neg_hi:[1,0,0]
	s_waitcnt lgkmcnt(1)
	v_pk_mul_f32 v[192:193], v[82:83], v[188:189]
	v_add_f32_e32 v198, v192, v193
	s_nop 1
	v_add_f32_dpp v198, v198, v198 quad_perm:[1,0,3,2] row_mask:0xf bank_mask:0xf bound_ctrl:1
	ds_write_b32 v100, v198 offset:15872
.Lrs_post:
	v_mov_b64_e32 v[56:57], v[82:83]
	s_waitcnt lgkmcnt(0)
	s_barrier
	ds_read_b128 v[60:63], v101
	ds_read_b128 v[64:67], v101 offset:16
	ds_read_b128 v[68:71], v101 offset:32
	ds_read_b128 v[162:165], v101 offset:48
	v_add_u32_e32 v170, s35, v90
	v_ashrrev_i32_e32 v171, 31, v170
	v_lshlrev_b64 v[170:171], 10, v[170:171]
	v_lshl_add_u64 v[170:171], v[102:103], 0, v[170:171]
	s_waitcnt lgkmcnt(2)
	v_add_f32_e32 v60, v60, v61
	v_add_f32_e32 v62, v62, v63
	v_add_f32_e32 v64, v64, v65
	v_add_f32_e32 v66, v66, v67
	v_add_f32_e32 v60, v60, v62
	v_add_f32_e32 v64, v64, v66
	s_waitcnt lgkmcnt(0)
	v_add_f32_e32 v68, v68, v69
	v_add_f32_e32 v70, v70, v71
	v_add_f32_e32 v162, v162, v163
	v_add_f32_e32 v164, v164, v165
	v_add_f32_e32 v68, v68, v70
	v_add_f32_e32 v162, v162, v164
	v_add_f32_e32 v60, v60, v64
	v_add_f32_e32 v68, v68, v162
	v_add_f32_e32 v60, v60, v68
	s_nop 1
	v_mov_b32_dpp v61, v60 quad_perm:[1,0,3,2] row_mask:0xf bank_mask:0xf bound_ctrl:1
	s_nop 0
	v_cvt_pk_bf16_f32 v16, v60, v61
	s_mov_b32 s26, 0x55555555
	s_mov_b32 s27, 0x55555555
	s_and_b64 exec, exec, s[26:27]
	global_atomic_pk_add_bf16 v[170:171], v16, off
	s_mov_b64 exec, -1
	s_andn2_b64 vcc, exec, s[28:29]
	s_cbranch_vccnz .LBB0_423
	s_and_saveexec_b64 s[26:27], s[6:7]
	s_cbranch_execz .LBB0_524
	s_and_saveexec_b64 s[28:29], s[18:19]
	s_xor_b64 s[28:29], exec, s[28:29]
	s_cbranch_execz .LBB0_522
	s_waitcnt vmcnt(1)
	v_lshlrev_b32_e32 v60, 16, v20
	v_and_b32_e32 v61, 0xffff0000, v20
	v_lshlrev_b32_e32 v62, 16, v21
	v_and_b32_e32 v63, 0xffff0000, v21
	v_lshlrev_b32_e32 v64, 16, v22
	v_and_b32_e32 v65, 0xffff0000, v22
	v_lshlrev_b32_e32 v66, 16, v23
	v_and_b32_e32 v67, 0xffff0000, v23
	ds_write_b128 v149, v[60:63]
	ds_write_b128 v149, v[64:67] offset:16
